# EpiVT store waits moved into bias-load branch + K-loop LDS-DMA loads use SGPR-base saddr form (no VALU 64-bit adds)
# speedup vs baseline: 1.0101x; 1.0101x over previous
.LBB0_453:
	s_add_u32 s24, s22, 0xfffc0080
	s_addc_u32 s25, s23, -1
	s_add_i32 s76, 0, 0x10000
	s_cmp_eq_u32 vcc_lo, 12
	s_cselect_b32 s29, s30, s25
	s_cselect_b32 s28, s31, s24
	v_add_u32_e32 v114, s76, v220
	s_cselect_b32 s25, s69, s99
	s_cselect_b32 s24, s75, s81
	s_add_i32 vcc_hi, 0, 0x14000
	ds_read_b128 v[106:109], v114
	ds_read_b128 v[110:113], v114 offset:1024
	ds_read_b128 v[128:131], v114 offset:2048
	ds_read_b128 v[132:135], v114 offset:3072
	v_add_u32_e32 v114, vcc_hi, v220
	ds_read_b128 v[136:139], v114
	ds_read_b128 v[158:161], v114 offset:1024
	ds_read_b128 v[162:165], v114 offset:2048
	ds_read_b128 v[166:169], v114 offset:3072
	s_add_i32 m0, s57, 0xc000
	ds_read_b128 v[170:173], v234
	ds_read_b128 v[174:177], v234 offset:1024
	ds_read_b128 v[178:181], v234 offset:2048
	ds_read_b128 v[198:201], v234 offset:3072
	ds_read_b128 v[202:205], v234 offset:4096
	ds_read_b128 v[206:209], v234 offset:5120
	ds_read_b128 v[210:213], v234 offset:6144
	ds_read_b128 v[214:217], v234 offset:7168
	global_load_lds_dwordx4 v194, s[22:23]
	s_add_i32 m0, s57, 0xe000
	s_nop 0
	global_load_lds_dwordx4 v196, s[22:23]
	s_waitcnt vmcnt(8)
	s_waitcnt lgkmcnt(0)
	s_barrier
	s_setprio 1
	s_waitcnt lgkmcnt(0)
	v_mfma_f32_16x16x32_bf16 v[124:127], v[106:109], v[170:173], v[124:127]
	v_mfma_f32_16x16x32_bf16 v[98:101], v[128:131], v[170:173], v[98:101]
	v_mfma_f32_16x16x32_bf16 v[154:157], v[106:109], v[178:181], v[154:157]
	v_mfma_f32_16x16x32_bf16 v[58:61], v[128:131], v[178:181], v[58:61]
	v_mfma_f32_16x16x32_bf16 v[146:149], v[106:109], v[202:205], v[146:149]
	v_mfma_f32_16x16x32_bf16 v[46:49], v[128:131], v[202:205], v[46:49]
	v_mfma_f32_16x16x32_bf16 v[102:105], v[106:109], v[210:213], v[102:105]
	v_mfma_f32_16x16x32_bf16 v[54:57], v[128:131], v[210:213], v[54:57]
	v_mfma_f32_16x16x32_bf16 v[124:127], v[110:113], v[174:177], v[124:127]
	v_mfma_f32_16x16x32_bf16 v[98:101], v[132:135], v[174:177], v[98:101]
	v_mfma_f32_16x16x32_bf16 v[154:157], v[110:113], v[198:201], v[154:157]
	v_mfma_f32_16x16x32_bf16 v[58:61], v[132:135], v[198:201], v[58:61]
	v_mfma_f32_16x16x32_bf16 v[146:149], v[110:113], v[206:209], v[146:149]
	v_mfma_f32_16x16x32_bf16 v[46:49], v[132:135], v[206:209], v[46:49]
	v_mfma_f32_16x16x32_bf16 v[102:105], v[110:113], v[214:217], v[102:105]
	v_mfma_f32_16x16x32_bf16 v[54:57], v[132:135], v[214:217], v[54:57]
	s_setprio 0
	s_setprio 1
	v_mfma_f32_16x16x32_bf16 v[120:123], v[136:139], v[170:173], v[120:123]
	v_mfma_f32_16x16x32_bf16 v[94:97], v[162:165], v[170:173], v[94:97]
	v_mfma_f32_16x16x32_bf16 v[150:153], v[136:139], v[178:181], v[150:153]
	v_mfma_f32_16x16x32_bf16 v[50:53], v[162:165], v[178:181], v[50:53]
	v_mfma_f32_16x16x32_bf16 v[140:143], v[136:139], v[202:205], v[142:145]
	v_mfma_f32_16x16x32_bf16 v[42:45], v[162:165], v[202:205], v[42:45]
	v_mfma_f32_16x16x32_bf16 v[114:117], v[136:139], v[210:213], v[116:119]
	v_mfma_f32_16x16x32_bf16 v[38:41], v[162:165], v[210:213], v[38:41]
	v_mfma_f32_16x16x32_bf16 v[120:123], v[158:161], v[174:177], v[120:123]
	v_mfma_f32_16x16x32_bf16 v[94:97], v[166:169], v[174:177], v[94:97]
	v_mfma_f32_16x16x32_bf16 v[150:153], v[158:161], v[198:201], v[150:153]
	v_mfma_f32_16x16x32_bf16 v[50:53], v[166:169], v[198:201], v[50:53]
	v_mfma_f32_16x16x32_bf16 v[140:143], v[158:161], v[206:209], v[140:143]
	v_mfma_f32_16x16x32_bf16 v[42:45], v[166:169], v[206:209], v[42:45]
	v_mfma_f32_16x16x32_bf16 v[114:117], v[158:161], v[214:217], v[114:117]
	v_mfma_f32_16x16x32_bf16 v[38:41], v[166:169], v[214:217], v[38:41]
	s_setprio 0
	s_barrier
	s_add_i32 s76, s76, s42
	s_mov_b32 m0, s76
	ds_read_b128 v[170:173], v234 offset:16384
	ds_read_b128 v[174:177], v234 offset:17408
	ds_read_b128 v[178:181], v234 offset:18432
	ds_read_b128 v[198:201], v234 offset:19456
	ds_read_b128 v[202:205], v234 offset:20480
	ds_read_b128 v[206:209], v234 offset:21504
	ds_read_b128 v[210:213], v234 offset:22528
	ds_read_b128 v[214:217], v234 offset:23552
	global_load_lds_dwordx4 v0, s[24:25]
	s_add_i32 m0, s76, 0x2000
	s_add_u32 s76, s24, 0x40000
	s_addc_u32 s77, s25, 0
	s_add_i32 vcc_hi, vcc_hi, s42
	global_load_lds_dwordx4 v192, s[24:25]
	s_mov_b32 m0, vcc_hi
	s_nop 0
	global_load_lds_dwordx4 v0, s[76:77]
	s_add_i32 m0, vcc_hi, 0x2000
	s_nop 0
	global_load_lds_dwordx4 v192, s[76:77]
	s_mov_b32 m0, s57
	s_nop 0
	global_load_lds_dwordx4 v188, s[28:29]
	s_mov_b32 m0, s66
	s_nop 0
	global_load_lds_dwordx4 v190, s[28:29]
	s_waitcnt vmcnt(8)
	s_waitcnt lgkmcnt(0)
	s_barrier
	s_setprio 1
	s_waitcnt lgkmcnt(0)
	v_mfma_f32_16x16x32_bf16 v[86:89], v[106:109], v[170:173], v[86:89]
	v_mfma_f32_16x16x32_bf16 v[30:33], v[128:131], v[170:173], v[30:33]
	v_mfma_f32_16x16x32_bf16 v[78:81], v[106:109], v[178:181], v[78:81]
	v_mfma_f32_16x16x32_bf16 v[22:25], v[128:131], v[178:181], v[22:25]
	v_mfma_f32_16x16x32_bf16 v[70:73], v[106:109], v[202:205], v[70:73]
	v_mfma_f32_16x16x32_bf16 v[14:17], v[128:131], v[202:205], v[14:17]
	v_mfma_f32_16x16x32_bf16 v[90:93], v[106:109], v[210:213], v[90:93]
	v_mfma_f32_16x16x32_bf16 v[34:37], v[128:131], v[210:213], v[34:37]
	v_mfma_f32_16x16x32_bf16 v[86:89], v[110:113], v[174:177], v[86:89]
	v_mfma_f32_16x16x32_bf16 v[30:33], v[132:135], v[174:177], v[30:33]
	v_mfma_f32_16x16x32_bf16 v[78:81], v[110:113], v[198:201], v[78:81]
	v_mfma_f32_16x16x32_bf16 v[22:25], v[132:135], v[198:201], v[22:25]
	v_mfma_f32_16x16x32_bf16 v[70:73], v[110:113], v[206:209], v[70:73]
	v_mfma_f32_16x16x32_bf16 v[14:17], v[132:135], v[206:209], v[14:17]
	v_mfma_f32_16x16x32_bf16 v[90:93], v[110:113], v[214:217], v[90:93]
	v_mfma_f32_16x16x32_bf16 v[34:37], v[132:135], v[214:217], v[34:37]
	s_setprio 0
	s_setprio 1
	v_mfma_f32_16x16x32_bf16 v[82:85], v[136:139], v[170:173], v[82:85]
	v_mfma_f32_16x16x32_bf16 v[26:29], v[162:165], v[170:173], v[26:29]
	v_mfma_f32_16x16x32_bf16 v[74:77], v[136:139], v[178:181], v[74:77]
	v_mfma_f32_16x16x32_bf16 v[18:21], v[162:165], v[178:181], v[18:21]
	v_mfma_f32_16x16x32_bf16 v[66:69], v[136:139], v[202:205], v[66:69]
	v_mfma_f32_16x16x32_bf16 v[10:13], v[162:165], v[202:205], v[10:13]
	v_mfma_f32_16x16x32_bf16 v[62:65], v[136:139], v[210:213], v[62:65]
	v_mfma_f32_16x16x32_bf16 v[6:9], v[162:165], v[210:213], v[6:9]
	v_mfma_f32_16x16x32_bf16 v[82:85], v[158:161], v[174:177], v[82:85]
	v_mfma_f32_16x16x32_bf16 v[26:29], v[166:169], v[174:177], v[26:29]
	v_mfma_f32_16x16x32_bf16 v[74:77], v[158:161], v[198:201], v[74:77]
	v_mfma_f32_16x16x32_bf16 v[18:21], v[166:169], v[198:201], v[18:21]
	v_mfma_f32_16x16x32_bf16 v[66:69], v[158:161], v[206:209], v[66:69]
	v_mfma_f32_16x16x32_bf16 v[10:13], v[166:169], v[206:209], v[10:13]
	v_mfma_f32_16x16x32_bf16 v[62:65], v[158:161], v[214:217], v[62:65]
	v_mfma_f32_16x16x32_bf16 v[6:9], v[166:169], v[214:217], v[6:9]
	s_setprio 0
	s_barrier
	s_add_i32 s76, 0, 0x18000
	v_add_u32_e32 v118, s76, v220
	s_add_i32 s77, 0, 0x1c000
	ds_read_b128 v[106:109], v118
	ds_read_b128 v[110:113], v118 offset:1024
	ds_read_b128 v[128:131], v118 offset:2048
	ds_read_b128 v[132:135], v118 offset:3072
	v_add_u32_e32 v118, s77, v220
	ds_read_b128 v[136:139], v118
	ds_read_b128 v[158:161], v118 offset:1024
	ds_read_b128 v[162:165], v118 offset:2048
	ds_read_b128 v[166:169], v118 offset:3072
	s_add_u32 s28, s28, 0x40000
	s_addc_u32 s29, s29, 0
	s_mov_b32 m0, s67
	ds_read_b128 v[170:173], v234 offset:32768
	ds_read_b128 v[174:177], v234 offset:33792
	ds_read_b128 v[178:181], v234 offset:34816
	ds_read_b128 v[198:201], v234 offset:35840
	ds_read_b128 v[202:205], v234 offset:36864
	ds_read_b128 v[206:209], v234 offset:37888
	ds_read_b128 v[210:213], v234 offset:38912
	ds_read_b128 v[214:217], v234 offset:39936
	global_load_lds_dwordx4 v188, s[28:29]
	s_mov_b32 m0, s44
	s_nop 0
	global_load_lds_dwordx4 v190, s[28:29]
	s_waitcnt vmcnt(8)
	s_waitcnt lgkmcnt(0)
	s_barrier
	s_setprio 1
	s_waitcnt lgkmcnt(0)
	v_mfma_f32_16x16x32_bf16 v[124:127], v[106:109], v[170:173], v[124:127]
	v_mfma_f32_16x16x32_bf16 v[98:101], v[128:131], v[170:173], v[98:101]
	v_mfma_f32_16x16x32_bf16 v[154:157], v[106:109], v[178:181], v[154:157]
	v_mfma_f32_16x16x32_bf16 v[58:61], v[128:131], v[178:181], v[58:61]
	v_mfma_f32_16x16x32_bf16 v[144:147], v[106:109], v[202:205], v[146:149]
	v_mfma_f32_16x16x32_bf16 v[46:49], v[128:131], v[202:205], v[46:49]
	v_mfma_f32_16x16x32_bf16 v[102:105], v[106:109], v[210:213], v[102:105]
	v_mfma_f32_16x16x32_bf16 v[54:57], v[128:131], v[210:213], v[54:57]
	v_mfma_f32_16x16x32_bf16 v[124:127], v[110:113], v[174:177], v[124:127]
	v_mfma_f32_16x16x32_bf16 v[98:101], v[132:135], v[174:177], v[98:101]
	v_mfma_f32_16x16x32_bf16 v[154:157], v[110:113], v[198:201], v[154:157]
	v_mfma_f32_16x16x32_bf16 v[58:61], v[132:135], v[198:201], v[58:61]
	v_mfma_f32_16x16x32_bf16 v[146:149], v[110:113], v[206:209], v[144:147]
	v_mfma_f32_16x16x32_bf16 v[46:49], v[132:135], v[206:209], v[46:49]
	v_mfma_f32_16x16x32_bf16 v[102:105], v[110:113], v[214:217], v[102:105]
	v_mfma_f32_16x16x32_bf16 v[54:57], v[132:135], v[214:217], v[54:57]
	s_setprio 0
	s_setprio 1
	v_mfma_f32_16x16x32_bf16 v[118:121], v[136:139], v[170:173], v[120:123]
	v_mfma_f32_16x16x32_bf16 v[94:97], v[162:165], v[170:173], v[94:97]
	v_mfma_f32_16x16x32_bf16 v[150:153], v[136:139], v[178:181], v[150:153]
	v_mfma_f32_16x16x32_bf16 v[50:53], v[162:165], v[178:181], v[50:53]
	v_mfma_f32_16x16x32_bf16 v[140:143], v[136:139], v[202:205], v[140:143]
	v_mfma_f32_16x16x32_bf16 v[42:45], v[162:165], v[202:205], v[42:45]
	v_mfma_f32_16x16x32_bf16 v[114:117], v[136:139], v[210:213], v[114:117]
	v_mfma_f32_16x16x32_bf16 v[38:41], v[162:165], v[210:213], v[38:41]
	v_mfma_f32_16x16x32_bf16 v[120:123], v[158:161], v[174:177], v[118:121]
	v_mfma_f32_16x16x32_bf16 v[94:97], v[166:169], v[174:177], v[94:97]
	v_mfma_f32_16x16x32_bf16 v[150:153], v[158:161], v[198:201], v[150:153]
	v_mfma_f32_16x16x32_bf16 v[50:53], v[166:169], v[198:201], v[50:53]
	v_mfma_f32_16x16x32_bf16 v[142:145], v[158:161], v[206:209], v[140:143]
	v_mfma_f32_16x16x32_bf16 v[42:45], v[166:169], v[206:209], v[42:45]
	v_mfma_f32_16x16x32_bf16 v[116:119], v[158:161], v[214:217], v[114:117]
	v_mfma_f32_16x16x32_bf16 v[38:41], v[166:169], v[214:217], v[38:41]
	s_setprio 0
	s_barrier
	s_add_i32 s100, s76, s42
	s_mov_b32 m0, s100
	ds_read_b128 v[170:173], v234 offset:49152
	ds_read_b128 v[174:177], v234 offset:50176
	ds_read_b128 v[178:181], v234 offset:51200
	ds_read_b128 v[198:201], v234 offset:52224
	ds_read_b128 v[202:205], v234 offset:53248
	ds_read_b128 v[206:209], v234 offset:54272
	ds_read_b128 v[210:213], v234 offset:55296
	ds_read_b128 v[214:217], v234 offset:56320
	s_add_u32 s24, s24, 0x80
	s_addc_u32 s25, s25, 0
	global_load_lds_dwordx4 v0, s[24:25]
	s_add_i32 m0, s100, 0x2000
	s_add_i32 s100, s77, s42
	global_load_lds_dwordx4 v192, s[24:25]
	s_add_u32 s24, s24, 0x40000
	s_addc_u32 s25, s25, 0
	s_mov_b32 m0, s100
	s_add_i32 s100, s100, 0x2000
	global_load_lds_dwordx4 v0, s[24:25]
	s_mov_b32 m0, s100
	s_add_u32 s28, s28, 0xfffc0080
	s_addc_u32 s29, s29, -1
	global_load_lds_dwordx4 v192, s[24:25]
	s_mov_b32 m0, s45
	s_nop 0
	global_load_lds_dwordx4 v188, s[28:29]
	s_mov_b32 m0, s70
	s_nop 0
	global_load_lds_dwordx4 v190, s[28:29]
	s_waitcnt vmcnt(8)
	s_waitcnt lgkmcnt(0)
	s_barrier
	s_setprio 1
	s_waitcnt lgkmcnt(0)
	v_mfma_f32_16x16x32_bf16 v[86:89], v[106:109], v[170:173], v[86:89]
	v_mfma_f32_16x16x32_bf16 v[30:33], v[128:131], v[170:173], v[30:33]
	v_mfma_f32_16x16x32_bf16 v[78:81], v[106:109], v[178:181], v[78:81]
	v_mfma_f32_16x16x32_bf16 v[22:25], v[128:131], v[178:181], v[22:25]
	v_mfma_f32_16x16x32_bf16 v[70:73], v[106:109], v[202:205], v[70:73]
	v_mfma_f32_16x16x32_bf16 v[14:17], v[128:131], v[202:205], v[14:17]
	v_mfma_f32_16x16x32_bf16 v[90:93], v[106:109], v[210:213], v[90:93]
	v_mfma_f32_16x16x32_bf16 v[34:37], v[128:131], v[210:213], v[34:37]
	v_mfma_f32_16x16x32_bf16 v[86:89], v[110:113], v[174:177], v[86:89]
	v_mfma_f32_16x16x32_bf16 v[30:33], v[132:135], v[174:177], v[30:33]
	v_mfma_f32_16x16x32_bf16 v[78:81], v[110:113], v[198:201], v[78:81]
	v_mfma_f32_16x16x32_bf16 v[22:25], v[132:135], v[198:201], v[22:25]
	v_mfma_f32_16x16x32_bf16 v[70:73], v[110:113], v[206:209], v[70:73]
	v_mfma_f32_16x16x32_bf16 v[14:17], v[132:135], v[206:209], v[14:17]
	v_mfma_f32_16x16x32_bf16 v[90:93], v[110:113], v[214:217], v[90:93]
	v_mfma_f32_16x16x32_bf16 v[34:37], v[132:135], v[214:217], v[34:37]
	s_setprio 0
	s_setprio 1
	v_mfma_f32_16x16x32_bf16 v[82:85], v[136:139], v[170:173], v[82:85]
	v_mfma_f32_16x16x32_bf16 v[26:29], v[162:165], v[170:173], v[26:29]
	v_mfma_f32_16x16x32_bf16 v[74:77], v[136:139], v[178:181], v[74:77]
	v_mfma_f32_16x16x32_bf16 v[18:21], v[162:165], v[178:181], v[18:21]
	v_mfma_f32_16x16x32_bf16 v[66:69], v[136:139], v[202:205], v[66:69]
	v_mfma_f32_16x16x32_bf16 v[10:13], v[162:165], v[202:205], v[10:13]
	v_mfma_f32_16x16x32_bf16 v[62:65], v[136:139], v[210:213], v[62:65]
	v_mfma_f32_16x16x32_bf16 v[6:9], v[162:165], v[210:213], v[6:9]
	v_mfma_f32_16x16x32_bf16 v[82:85], v[158:161], v[174:177], v[82:85]
	v_mfma_f32_16x16x32_bf16 v[26:29], v[166:169], v[174:177], v[26:29]
	v_mfma_f32_16x16x32_bf16 v[74:77], v[158:161], v[198:201], v[74:77]
	v_mfma_f32_16x16x32_bf16 v[18:21], v[166:169], v[198:201], v[18:21]
	v_mfma_f32_16x16x32_bf16 v[66:69], v[158:161], v[206:209], v[66:69]
	v_mfma_f32_16x16x32_bf16 v[10:13], v[166:169], v[206:209], v[10:13]
	v_mfma_f32_16x16x32_bf16 v[62:65], v[158:161], v[214:217], v[62:65]
	v_mfma_f32_16x16x32_bf16 v[6:9], v[166:169], v[214:217], v[6:9]
	s_setprio 0
	s_barrier
	s_add_i32 vcc_lo, vcc_lo, 2
	s_add_u32 s22, s22, 0x100
	s_addc_u32 s23, s23, 0
	s_add_u32 s81, s81, 0x100
	s_addc_u32 s99, s99, 0
	s_cmp_gt_u32 vcc_lo, 13
	s_cbranch_scc0 .LBB0_453
	s_and_b64 vcc, exec, s[26:27]
	s_cbranch_vccz .LBB0_456
	s_barrier

.LBB0_711:
	s_add_u32 s8, s10, 0xfffc0080
	s_addc_u32 s9, s11, -1
	s_add_i32 s67, 0, 0x10000
	s_cmp_eq_u32 s51, 12
	s_cselect_b32 s13, s25, s9
	s_cselect_b32 s12, s27, s8
	s_cselect_b32 s9, s29, s50
	s_cselect_b32 s8, s44, s45
	s_add_i32 s72, 0, 0x14000
	v_add_u32_e32 v146, s67, v245
	v_add_u32_e32 v162, s72, v245
	ds_read_b128 v[134:137], v146
	ds_read_b128 v[138:141], v146 offset:1024
	ds_read_b128 v[142:145], v146 offset:2048
	ds_read_b128 v[146:149], v146 offset:3072
	ds_read_b128 v[150:153], v162
	ds_read_b128 v[154:157], v162 offset:1024
	ds_read_b128 v[158:161], v162 offset:2048
	ds_read_b128 v[162:165], v162 offset:3072
	s_add_i32 m0, s68, 0xc000
	ds_read_b128 v[166:169], v247
	ds_read_b128 v[170:173], v247 offset:1024
	ds_read_b128 v[174:177], v247 offset:2048
	ds_read_b128 v[178:181], v247 offset:3072
	ds_read_b128 v[196:199], v247 offset:4096
	ds_read_b128 v[200:203], v247 offset:5120
	ds_read_b128 v[204:207], v247 offset:6144
	ds_read_b128 v[208:211], v247 offset:7168
	global_load_lds_dwordx4 v192, s[10:11]
	s_add_i32 m0, s68, 0xe000
	s_nop 0
	global_load_lds_dwordx4 v194, s[10:11]
	s_waitcnt vmcnt(8)
	s_waitcnt lgkmcnt(0)
	s_barrier
	s_setprio 1
	s_waitcnt lgkmcnt(0)
	v_mfma_f32_16x16x32_bf16 v[130:133], v[134:137], v[166:169], v[130:133]
	v_mfma_f32_16x16x32_bf16 v[126:129], v[142:145], v[166:169], v[126:129]
	v_mfma_f32_16x16x32_bf16 v[114:117], v[134:137], v[174:177], v[114:117]
	v_mfma_f32_16x16x32_bf16 v[110:113], v[142:145], v[174:177], v[110:113]
	v_mfma_f32_16x16x32_bf16 v[98:101], v[134:137], v[196:199], v[98:101]
	v_mfma_f32_16x16x32_bf16 v[94:97], v[142:145], v[196:199], v[94:97]
	v_mfma_f32_16x16x32_bf16 v[82:85], v[134:137], v[204:207], v[82:85]
	v_mfma_f32_16x16x32_bf16 v[78:81], v[142:145], v[204:207], v[78:81]
	v_mfma_f32_16x16x32_bf16 v[130:133], v[138:141], v[170:173], v[130:133]
	v_mfma_f32_16x16x32_bf16 v[126:129], v[146:149], v[170:173], v[126:129]
	v_mfma_f32_16x16x32_bf16 v[114:117], v[138:141], v[178:181], v[114:117]
	v_mfma_f32_16x16x32_bf16 v[110:113], v[146:149], v[178:181], v[110:113]
	v_mfma_f32_16x16x32_bf16 v[98:101], v[138:141], v[200:203], v[98:101]
	v_mfma_f32_16x16x32_bf16 v[94:97], v[146:149], v[200:203], v[94:97]
	v_mfma_f32_16x16x32_bf16 v[82:85], v[138:141], v[208:211], v[82:85]
	v_mfma_f32_16x16x32_bf16 v[78:81], v[146:149], v[208:211], v[78:81]
	s_setprio 0
	s_setprio 1
	v_mfma_f32_16x16x32_bf16 v[122:125], v[150:153], v[166:169], v[122:125]
	v_mfma_f32_16x16x32_bf16 v[118:121], v[158:161], v[166:169], v[118:121]
	v_mfma_f32_16x16x32_bf16 v[106:109], v[150:153], v[174:177], v[106:109]
	v_mfma_f32_16x16x32_bf16 v[102:105], v[158:161], v[174:177], v[102:105]
	v_mfma_f32_16x16x32_bf16 v[90:93], v[150:153], v[196:199], v[90:93]
	v_mfma_f32_16x16x32_bf16 v[86:89], v[158:161], v[196:199], v[86:89]
	v_mfma_f32_16x16x32_bf16 v[74:77], v[150:153], v[204:207], v[74:77]
	v_mfma_f32_16x16x32_bf16 v[70:73], v[158:161], v[204:207], v[70:73]
	v_mfma_f32_16x16x32_bf16 v[122:125], v[154:157], v[170:173], v[122:125]
	v_mfma_f32_16x16x32_bf16 v[118:121], v[162:165], v[170:173], v[118:121]
	v_mfma_f32_16x16x32_bf16 v[106:109], v[154:157], v[178:181], v[106:109]
	v_mfma_f32_16x16x32_bf16 v[102:105], v[162:165], v[178:181], v[102:105]
	v_mfma_f32_16x16x32_bf16 v[90:93], v[154:157], v[200:203], v[90:93]
	v_mfma_f32_16x16x32_bf16 v[86:89], v[162:165], v[200:203], v[86:89]
	v_mfma_f32_16x16x32_bf16 v[74:77], v[154:157], v[208:211], v[74:77]
	v_mfma_f32_16x16x32_bf16 v[70:73], v[162:165], v[208:211], v[70:73]
	s_setprio 0
	s_barrier
	s_add_i32 s67, s67, s63
	s_mov_b32 m0, s67
	ds_read_b128 v[166:169], v247 offset:16384
	ds_read_b128 v[170:173], v247 offset:17408
	ds_read_b128 v[174:177], v247 offset:18432
	ds_read_b128 v[178:181], v247 offset:19456
	ds_read_b128 v[196:199], v247 offset:20480
	ds_read_b128 v[200:203], v247 offset:21504
	ds_read_b128 v[204:207], v247 offset:22528
	ds_read_b128 v[208:211], v247 offset:23552
	global_load_lds_dwordx4 v0, s[8:9]
	s_add_i32 m0, s67, 0x2000
	s_add_u32 s70, s8, 0x40000
	s_addc_u32 s71, s9, 0
	s_add_i32 s67, s72, s63
	global_load_lds_dwordx4 v190, s[8:9]
	s_mov_b32 m0, s67
	s_nop 0
	global_load_lds_dwordx4 v0, s[70:71]
	s_add_i32 m0, s67, 0x2000
	s_nop 0
	global_load_lds_dwordx4 v190, s[70:71]
	s_mov_b32 m0, s68
	s_nop 0
	global_load_lds_dwordx4 v182, s[12:13]
	s_mov_b32 m0, s69
	s_nop 0
	global_load_lds_dwordx4 v188, s[12:13]
	s_waitcnt vmcnt(8)
	s_waitcnt lgkmcnt(0)
	s_barrier
	s_setprio 1
	s_waitcnt lgkmcnt(0)
	v_mfma_f32_16x16x32_bf16 v[66:69], v[134:137], v[166:169], v[66:69]
	v_mfma_f32_16x16x32_bf16 v[62:65], v[142:145], v[166:169], v[62:65]
	v_mfma_f32_16x16x32_bf16 v[50:53], v[134:137], v[174:177], v[50:53]
	v_mfma_f32_16x16x32_bf16 v[46:49], v[142:145], v[174:177], v[46:49]
	v_mfma_f32_16x16x32_bf16 v[34:37], v[134:137], v[196:199], v[34:37]
	v_mfma_f32_16x16x32_bf16 v[30:33], v[142:145], v[196:199], v[30:33]
	v_mfma_f32_16x16x32_bf16 v[18:21], v[134:137], v[204:207], v[18:21]
	v_mfma_f32_16x16x32_bf16 v[14:17], v[142:145], v[204:207], v[14:17]
	v_mfma_f32_16x16x32_bf16 v[66:69], v[138:141], v[170:173], v[66:69]
	v_mfma_f32_16x16x32_bf16 v[62:65], v[146:149], v[170:173], v[62:65]
	v_mfma_f32_16x16x32_bf16 v[50:53], v[138:141], v[178:181], v[50:53]
	v_mfma_f32_16x16x32_bf16 v[46:49], v[146:149], v[178:181], v[46:49]
	v_mfma_f32_16x16x32_bf16 v[34:37], v[138:141], v[200:203], v[34:37]
	v_mfma_f32_16x16x32_bf16 v[30:33], v[146:149], v[200:203], v[30:33]
	v_mfma_f32_16x16x32_bf16 v[18:21], v[138:141], v[208:211], v[18:21]
	v_mfma_f32_16x16x32_bf16 v[14:17], v[146:149], v[208:211], v[14:17]
	s_setprio 0
	s_setprio 1
	v_mfma_f32_16x16x32_bf16 v[58:61], v[150:153], v[166:169], v[58:61]
	v_mfma_f32_16x16x32_bf16 v[54:57], v[158:161], v[166:169], v[54:57]
	v_mfma_f32_16x16x32_bf16 v[42:45], v[150:153], v[174:177], v[42:45]
	v_mfma_f32_16x16x32_bf16 v[38:41], v[158:161], v[174:177], v[38:41]
	v_mfma_f32_16x16x32_bf16 v[26:29], v[150:153], v[196:199], v[26:29]
	v_mfma_f32_16x16x32_bf16 v[22:25], v[158:161], v[196:199], v[22:25]
	v_mfma_f32_16x16x32_bf16 v[10:13], v[150:153], v[204:207], v[10:13]
	v_mfma_f32_16x16x32_bf16 v[6:9], v[158:161], v[204:207], v[6:9]
	v_mfma_f32_16x16x32_bf16 v[58:61], v[154:157], v[170:173], v[58:61]
	v_mfma_f32_16x16x32_bf16 v[54:57], v[162:165], v[170:173], v[54:57]
	v_mfma_f32_16x16x32_bf16 v[42:45], v[154:157], v[178:181], v[42:45]
	v_mfma_f32_16x16x32_bf16 v[38:41], v[162:165], v[178:181], v[38:41]
	v_mfma_f32_16x16x32_bf16 v[26:29], v[154:157], v[200:203], v[26:29]
	v_mfma_f32_16x16x32_bf16 v[22:25], v[162:165], v[200:203], v[22:25]
	v_mfma_f32_16x16x32_bf16 v[10:13], v[154:157], v[208:211], v[10:13]
	v_mfma_f32_16x16x32_bf16 v[6:9], v[162:165], v[208:211], v[6:9]
	s_setprio 0
	s_barrier
	s_add_i32 s67, 0, 0x18000
	s_add_i32 s70, 0, 0x1c000
	v_add_u32_e32 v146, s67, v245
	v_add_u32_e32 v162, s70, v245
	ds_read_b128 v[134:137], v146
	ds_read_b128 v[138:141], v146 offset:1024
	ds_read_b128 v[142:145], v146 offset:2048
	ds_read_b128 v[146:149], v146 offset:3072
	ds_read_b128 v[150:153], v162
	ds_read_b128 v[154:157], v162 offset:1024
	ds_read_b128 v[158:161], v162 offset:2048
	ds_read_b128 v[162:165], v162 offset:3072
	s_add_u32 s12, s12, 0x40000
	s_addc_u32 s13, s13, 0
	s_mov_b32 m0, s78
	ds_read_b128 v[166:169], v247 offset:32768
	ds_read_b128 v[170:173], v247 offset:33792
	ds_read_b128 v[174:177], v247 offset:34816
	ds_read_b128 v[178:181], v247 offset:35840
	ds_read_b128 v[196:199], v247 offset:36864
	ds_read_b128 v[200:203], v247 offset:37888
	ds_read_b128 v[204:207], v247 offset:38912
	ds_read_b128 v[208:211], v247 offset:39936
	global_load_lds_dwordx4 v182, s[12:13]
	s_mov_b32 m0, s79
	s_nop 0
	global_load_lds_dwordx4 v188, s[12:13]
	s_waitcnt vmcnt(8)
	s_waitcnt lgkmcnt(0)
	s_barrier
	s_setprio 1
	s_waitcnt lgkmcnt(0)
	v_mfma_f32_16x16x32_bf16 v[130:133], v[134:137], v[166:169], v[130:133]
	v_mfma_f32_16x16x32_bf16 v[126:129], v[142:145], v[166:169], v[126:129]
	v_mfma_f32_16x16x32_bf16 v[114:117], v[134:137], v[174:177], v[114:117]
	v_mfma_f32_16x16x32_bf16 v[110:113], v[142:145], v[174:177], v[110:113]
	v_mfma_f32_16x16x32_bf16 v[98:101], v[134:137], v[196:199], v[98:101]
	v_mfma_f32_16x16x32_bf16 v[94:97], v[142:145], v[196:199], v[94:97]
	v_mfma_f32_16x16x32_bf16 v[82:85], v[134:137], v[204:207], v[82:85]
	v_mfma_f32_16x16x32_bf16 v[78:81], v[142:145], v[204:207], v[78:81]
	v_mfma_f32_16x16x32_bf16 v[130:133], v[138:141], v[170:173], v[130:133]
	v_mfma_f32_16x16x32_bf16 v[126:129], v[146:149], v[170:173], v[126:129]
	v_mfma_f32_16x16x32_bf16 v[114:117], v[138:141], v[178:181], v[114:117]
	v_mfma_f32_16x16x32_bf16 v[110:113], v[146:149], v[178:181], v[110:113]
	v_mfma_f32_16x16x32_bf16 v[98:101], v[138:141], v[200:203], v[98:101]
	v_mfma_f32_16x16x32_bf16 v[94:97], v[146:149], v[200:203], v[94:97]
	v_mfma_f32_16x16x32_bf16 v[82:85], v[138:141], v[208:211], v[82:85]
	v_mfma_f32_16x16x32_bf16 v[78:81], v[146:149], v[208:211], v[78:81]
	s_setprio 0
	s_setprio 1
	v_mfma_f32_16x16x32_bf16 v[122:125], v[150:153], v[166:169], v[122:125]
	v_mfma_f32_16x16x32_bf16 v[118:121], v[158:161], v[166:169], v[118:121]
	v_mfma_f32_16x16x32_bf16 v[106:109], v[150:153], v[174:177], v[106:109]
	v_mfma_f32_16x16x32_bf16 v[102:105], v[158:161], v[174:177], v[102:105]
	v_mfma_f32_16x16x32_bf16 v[90:93], v[150:153], v[196:199], v[90:93]
	v_mfma_f32_16x16x32_bf16 v[86:89], v[158:161], v[196:199], v[86:89]
	v_mfma_f32_16x16x32_bf16 v[74:77], v[150:153], v[204:207], v[74:77]
	v_mfma_f32_16x16x32_bf16 v[70:73], v[158:161], v[204:207], v[70:73]
	v_mfma_f32_16x16x32_bf16 v[122:125], v[154:157], v[170:173], v[122:125]
	v_mfma_f32_16x16x32_bf16 v[118:121], v[162:165], v[170:173], v[118:121]
	v_mfma_f32_16x16x32_bf16 v[106:109], v[154:157], v[178:181], v[106:109]
	v_mfma_f32_16x16x32_bf16 v[102:105], v[162:165], v[178:181], v[102:105]
	v_mfma_f32_16x16x32_bf16 v[90:93], v[154:157], v[200:203], v[90:93]
	v_mfma_f32_16x16x32_bf16 v[86:89], v[162:165], v[200:203], v[86:89]
	v_mfma_f32_16x16x32_bf16 v[74:77], v[154:157], v[208:211], v[74:77]
	v_mfma_f32_16x16x32_bf16 v[70:73], v[162:165], v[208:211], v[70:73]
	s_setprio 0
	s_barrier
	s_add_i32 s100, s67, s63
	s_mov_b32 m0, s100
	ds_read_b128 v[166:169], v247 offset:49152
	ds_read_b128 v[170:173], v247 offset:50176
	ds_read_b128 v[174:177], v247 offset:51200
	ds_read_b128 v[178:181], v247 offset:52224
	ds_read_b128 v[196:199], v247 offset:53248
	ds_read_b128 v[200:203], v247 offset:54272
	ds_read_b128 v[204:207], v247 offset:55296
	ds_read_b128 v[208:211], v247 offset:56320
	s_add_u32 s8, s8, 0x80
	s_addc_u32 s9, s9, 0
	global_load_lds_dwordx4 v0, s[8:9]
	s_add_i32 m0, s100, 0x2000
	s_add_i32 s100, s70, s63
	global_load_lds_dwordx4 v190, s[8:9]
	s_add_u32 s8, s8, 0x40000
	s_addc_u32 s9, s9, 0
	s_mov_b32 m0, s100
	s_add_i32 s100, s100, 0x2000
	global_load_lds_dwordx4 v0, s[8:9]
	s_mov_b32 m0, s100
	s_add_u32 s12, s12, 0xfffc0080
	s_addc_u32 s13, s13, -1
	global_load_lds_dwordx4 v190, s[8:9]
	s_mov_b32 m0, s80
	s_nop 0
	global_load_lds_dwordx4 v182, s[12:13]
	s_mov_b32 m0, s81
	s_nop 0
	global_load_lds_dwordx4 v188, s[12:13]
	s_waitcnt vmcnt(8)
	s_waitcnt lgkmcnt(0)
	s_barrier
	s_setprio 1
	s_waitcnt lgkmcnt(0)
	v_mfma_f32_16x16x32_bf16 v[66:69], v[134:137], v[166:169], v[66:69]
	v_mfma_f32_16x16x32_bf16 v[62:65], v[142:145], v[166:169], v[62:65]
	v_mfma_f32_16x16x32_bf16 v[50:53], v[134:137], v[174:177], v[50:53]
	v_mfma_f32_16x16x32_bf16 v[46:49], v[142:145], v[174:177], v[46:49]
	v_mfma_f32_16x16x32_bf16 v[34:37], v[134:137], v[196:199], v[34:37]
	v_mfma_f32_16x16x32_bf16 v[30:33], v[142:145], v[196:199], v[30:33]
	v_mfma_f32_16x16x32_bf16 v[18:21], v[134:137], v[204:207], v[18:21]
	v_mfma_f32_16x16x32_bf16 v[14:17], v[142:145], v[204:207], v[14:17]
	v_mfma_f32_16x16x32_bf16 v[66:69], v[138:141], v[170:173], v[66:69]
	v_mfma_f32_16x16x32_bf16 v[62:65], v[146:149], v[170:173], v[62:65]
	v_mfma_f32_16x16x32_bf16 v[50:53], v[138:141], v[178:181], v[50:53]
	v_mfma_f32_16x16x32_bf16 v[46:49], v[146:149], v[178:181], v[46:49]
	v_mfma_f32_16x16x32_bf16 v[34:37], v[138:141], v[200:203], v[34:37]
	v_mfma_f32_16x16x32_bf16 v[30:33], v[146:149], v[200:203], v[30:33]
	v_mfma_f32_16x16x32_bf16 v[18:21], v[138:141], v[208:211], v[18:21]
	v_mfma_f32_16x16x32_bf16 v[14:17], v[146:149], v[208:211], v[14:17]
	s_setprio 0
	s_setprio 1
	v_mfma_f32_16x16x32_bf16 v[58:61], v[150:153], v[166:169], v[58:61]
	v_mfma_f32_16x16x32_bf16 v[54:57], v[158:161], v[166:169], v[54:57]
	v_mfma_f32_16x16x32_bf16 v[42:45], v[150:153], v[174:177], v[42:45]
	v_mfma_f32_16x16x32_bf16 v[38:41], v[158:161], v[174:177], v[38:41]
	v_mfma_f32_16x16x32_bf16 v[26:29], v[150:153], v[196:199], v[26:29]
	v_mfma_f32_16x16x32_bf16 v[22:25], v[158:161], v[196:199], v[22:25]
	v_mfma_f32_16x16x32_bf16 v[10:13], v[150:153], v[204:207], v[10:13]
	v_mfma_f32_16x16x32_bf16 v[6:9], v[158:161], v[204:207], v[6:9]
	v_mfma_f32_16x16x32_bf16 v[58:61], v[154:157], v[170:173], v[58:61]
	v_mfma_f32_16x16x32_bf16 v[54:57], v[162:165], v[170:173], v[54:57]
	v_mfma_f32_16x16x32_bf16 v[42:45], v[154:157], v[178:181], v[42:45]
	v_mfma_f32_16x16x32_bf16 v[38:41], v[162:165], v[178:181], v[38:41]
	v_mfma_f32_16x16x32_bf16 v[26:29], v[154:157], v[200:203], v[26:29]
	v_mfma_f32_16x16x32_bf16 v[22:25], v[162:165], v[200:203], v[22:25]
	v_mfma_f32_16x16x32_bf16 v[10:13], v[154:157], v[208:211], v[10:13]
	v_mfma_f32_16x16x32_bf16 v[6:9], v[162:165], v[208:211], v[6:9]
	s_setprio 0
	s_barrier
	s_add_i32 s51, s51, 2
	s_add_u32 s10, s10, 0x100
	s_addc_u32 s11, s11, 0
	s_add_u32 s45, s45, 0x100
	s_addc_u32 s50, s50, 0
	s_cmp_gt_u32 s51, 13
	s_cbranch_scc0 .LBB0_711
	s_and_b64 vcc, exec, s[20:21]
	s_cbranch_vccz .LBB0_714
	s_barrier

.LBB0_723:
	v_lshl_add_u64 v[146:147], v[166:167], 1, s[22:23]
	v_lshlrev_b64 v[152:153], 16, v[198:199]
	v_cvt_pk_bf16_f32 v148, v136, v137
	v_lshl_add_u64 v[170:171], v[146:147], 0, v[152:153]
	v_cvt_pk_bf16_f32 v149, v134, v135
	v_cvt_pk_bf16_f32 v150, v140, v141
	v_cvt_pk_bf16_f32 v151, v138, v139
	global_store_dwordx4 v[170:171], v[148:151], off
	s_andn2_b64 vcc, exec, s[50:51]
	v_lshl_add_u64 v[168:169], v[198:199], 2, s[26:27]
	v_cndmask_b32_e64 v148, 0, 1, s[50:51]
	v_cmp_ne_u32_e64 s[12:13], 1, v148
	s_cbranch_vccnz .LBB0_725
	global_load_dword v154, v[168:169], off offset:64
	s_waitcnt vmcnt(0)
	s_branch .LBB0_726

.LBB0_726:
	v_pk_fma_f32 v[150:151], v[116:117], v[144:145], v[154:155] op_sel_hi:[1,1,0]
	v_pk_fma_f32 v[148:149], v[114:115], v[162:163], v[154:155] op_sel_hi:[1,1,0]
	v_pk_fma_f32 v[152:153], v[112:113], v[142:143], v[154:155] op_sel_hi:[1,1,0]
	s_and_b64 vcc, exec, s[10:11]
	v_pk_fma_f32 v[154:155], v[110:111], v[158:159], v[154:155] op_sel_hi:[1,1,0]
	s_cbranch_vccnz .LBB0_728
	v_pk_mul_f32 v[156:157], v[150:151], v[150:151]
	v_pk_mul_f32 v[160:161], v[148:149], v[148:149]
	v_mov_b64_e32 v[164:165], s[88:89]
	v_pk_fma_f32 v[160:161], v[160:161], s[96:97], v[164:165] op_sel_hi:[1,0,0] neg_lo:[1,0,0] neg_hi:[1,0,0]
	v_pk_fma_f32 v[156:157], v[156:157], s[96:97], v[164:165] op_sel_hi:[1,0,0] neg_lo:[1,0,0] neg_hi:[1,0,0]
	v_pk_mul_f32 v[160:161], v[148:149], v[160:161]
	v_pk_mul_f32 v[156:157], v[150:151], v[156:157]
	v_exp_f32_e32 v160, v160
	v_exp_f32_e32 v161, v161
	v_exp_f32_e32 v156, v156
	v_exp_f32_e32 v157, v157
	v_pk_add_f32 v[160:161], v[160:161], 1.0 op_sel_hi:[1,0]
	s_nop 0
	v_rcp_f32_e32 v160, v160
	v_pk_add_f32 v[156:157], v[156:157], 1.0 op_sel_hi:[1,0]
	v_rcp_f32_e32 v161, v161
	v_rcp_f32_e32 v156, v156
	v_rcp_f32_e32 v157, v157
	v_pk_mul_f32 v[148:149], v[148:149], v[160:161]
	v_pk_mul_f32 v[160:161], v[154:155], v[154:155]
	v_pk_mul_f32 v[150:151], v[150:151], v[156:157]
	v_pk_mul_f32 v[156:157], v[152:153], v[152:153]
	v_pk_fma_f32 v[160:161], v[160:161], s[96:97], v[164:165] op_sel_hi:[1,0,0] neg_lo:[1,0,0] neg_hi:[1,0,0]
	v_pk_fma_f32 v[156:157], v[156:157], s[96:97], v[164:165] op_sel_hi:[1,0,0] neg_lo:[1,0,0] neg_hi:[1,0,0]
	v_pk_mul_f32 v[160:161], v[154:155], v[160:161]
	v_pk_mul_f32 v[156:157], v[152:153], v[156:157]
	v_exp_f32_e32 v160, v160
	v_exp_f32_e32 v161, v161
	v_exp_f32_e32 v156, v156
	v_exp_f32_e32 v157, v157
	v_pk_add_f32 v[160:161], v[160:161], 1.0 op_sel_hi:[1,0]
	s_nop 0
	v_rcp_f32_e32 v160, v160
	v_pk_add_f32 v[156:157], v[156:157], 1.0 op_sel_hi:[1,0]
	v_rcp_f32_e32 v161, v161
	v_rcp_f32_e32 v156, v156
	v_rcp_f32_e32 v157, v157
	v_pk_mul_f32 v[154:155], v[154:155], v[160:161]
	v_pk_mul_f32 v[152:153], v[152:153], v[156:157]
.LBB0_728:
	v_or_b32_e32 v156, 16, v198
	v_ashrrev_i32_e32 v157, 31, v156
	v_lshlrev_b64 v[156:157], 16, v[156:157]
	v_lshl_add_u64 v[172:173], v[146:147], 0, v[156:157]
	s_and_b64 vcc, exec, s[12:13]
	v_cvt_pk_bf16_f32 v174, v148, v149
	v_cvt_pk_bf16_f32 v175, v150, v151
	v_cvt_pk_bf16_f32 v176, v154, v155
	v_cvt_pk_bf16_f32 v177, v152, v153
	global_store_dwordx4 v[172:173], v[174:177], off
	s_cbranch_vccnz .LBB0_730
	global_load_dword v174, v[168:169], off offset:128
	s_waitcnt vmcnt(0)
	s_branch .LBB0_731

.LBB0_731:
	v_pk_fma_f32 v[160:161], v[100:101], v[144:145], v[174:175] op_sel_hi:[1,1,0]
	v_pk_fma_f32 v[156:157], v[98:99], v[162:163], v[174:175] op_sel_hi:[1,1,0]
	v_pk_fma_f32 v[164:165], v[96:97], v[142:143], v[174:175] op_sel_hi:[1,1,0]
	s_and_b64 vcc, exec, s[10:11]
	v_pk_fma_f32 v[200:201], v[94:95], v[158:159], v[174:175] op_sel_hi:[1,1,0]
	s_cbranch_vccnz .LBB0_733
	v_pk_mul_f32 v[174:175], v[160:161], v[160:161]
	v_pk_mul_f32 v[176:177], v[156:157], v[156:157]
	v_mov_b64_e32 v[178:179], s[88:89]
	v_pk_fma_f32 v[176:177], v[176:177], s[96:97], v[178:179] op_sel_hi:[1,0,0] neg_lo:[1,0,0] neg_hi:[1,0,0]
	v_pk_fma_f32 v[174:175], v[174:175], s[96:97], v[178:179] op_sel_hi:[1,0,0] neg_lo:[1,0,0] neg_hi:[1,0,0]
	v_pk_mul_f32 v[176:177], v[156:157], v[176:177]
	v_pk_mul_f32 v[174:175], v[160:161], v[174:175]
	v_exp_f32_e32 v176, v176
	v_exp_f32_e32 v177, v177
	v_exp_f32_e32 v174, v174
	v_exp_f32_e32 v175, v175
	v_pk_add_f32 v[176:177], v[176:177], 1.0 op_sel_hi:[1,0]
	s_nop 0
	v_rcp_f32_e32 v176, v176
	v_pk_add_f32 v[174:175], v[174:175], 1.0 op_sel_hi:[1,0]
	v_rcp_f32_e32 v177, v177
	v_rcp_f32_e32 v174, v174
	v_rcp_f32_e32 v175, v175
	v_pk_mul_f32 v[156:157], v[156:157], v[176:177]
	v_pk_mul_f32 v[176:177], v[200:201], v[200:201]
	v_pk_mul_f32 v[160:161], v[160:161], v[174:175]
	v_pk_mul_f32 v[174:175], v[164:165], v[164:165]
	v_pk_fma_f32 v[176:177], v[176:177], s[96:97], v[178:179] op_sel_hi:[1,0,0] neg_lo:[1,0,0] neg_hi:[1,0,0]
	v_pk_fma_f32 v[174:175], v[174:175], s[96:97], v[178:179] op_sel_hi:[1,0,0] neg_lo:[1,0,0] neg_hi:[1,0,0]
	v_pk_mul_f32 v[176:177], v[200:201], v[176:177]
	v_pk_mul_f32 v[174:175], v[164:165], v[174:175]
	v_exp_f32_e32 v176, v176
	v_exp_f32_e32 v177, v177
	v_exp_f32_e32 v174, v174
	v_exp_f32_e32 v175, v175
	v_pk_add_f32 v[176:177], v[176:177], 1.0 op_sel_hi:[1,0]
	s_nop 0
	v_rcp_f32_e32 v176, v176
	v_pk_add_f32 v[174:175], v[174:175], 1.0 op_sel_hi:[1,0]
	v_rcp_f32_e32 v177, v177
	v_rcp_f32_e32 v174, v174
	v_rcp_f32_e32 v175, v175
	v_pk_mul_f32 v[200:201], v[200:201], v[176:177]
	v_pk_mul_f32 v[164:165], v[164:165], v[174:175]
.LBB0_733:
	v_or_b32_e32 v174, 32, v198
	v_ashrrev_i32_e32 v175, 31, v174
	v_lshlrev_b64 v[174:175], 16, v[174:175]
	v_lshl_add_u64 v[174:175], v[146:147], 0, v[174:175]
	s_and_b64 vcc, exec, s[12:13]
	v_cvt_pk_bf16_f32 v176, v156, v157
	v_cvt_pk_bf16_f32 v177, v160, v161
	v_cvt_pk_bf16_f32 v178, v200, v201
	v_cvt_pk_bf16_f32 v179, v164, v165
	global_store_dwordx4 v[174:175], v[176:179], off
	s_cbranch_vccnz .LBB0_735
	global_load_dword v176, v[168:169], off offset:192
	s_waitcnt vmcnt(0)
	s_branch .LBB0_736

.LBB0_736:
	v_pk_fma_f32 v[204:205], v[84:85], v[144:145], v[176:177] op_sel_hi:[1,1,0]
	v_pk_fma_f32 v[202:203], v[82:83], v[162:163], v[176:177] op_sel_hi:[1,1,0]
	v_pk_fma_f32 v[206:207], v[80:81], v[142:143], v[176:177] op_sel_hi:[1,1,0]
	s_and_b64 vcc, exec, s[10:11]
	v_pk_fma_f32 v[208:209], v[78:79], v[158:159], v[176:177] op_sel_hi:[1,1,0]
	s_cbranch_vccnz .LBB0_738
	v_pk_mul_f32 v[176:177], v[204:205], v[204:205]
	v_pk_mul_f32 v[178:179], v[202:203], v[202:203]
	v_mov_b64_e32 v[180:181], s[88:89]
	v_pk_fma_f32 v[178:179], v[178:179], s[96:97], v[180:181] op_sel_hi:[1,0,0] neg_lo:[1,0,0] neg_hi:[1,0,0]
	v_pk_fma_f32 v[176:177], v[176:177], s[96:97], v[180:181] op_sel_hi:[1,0,0] neg_lo:[1,0,0] neg_hi:[1,0,0]
	v_pk_mul_f32 v[178:179], v[202:203], v[178:179]
	v_pk_mul_f32 v[176:177], v[204:205], v[176:177]
	v_exp_f32_e32 v178, v178
	v_exp_f32_e32 v179, v179
	v_exp_f32_e32 v176, v176
	v_exp_f32_e32 v177, v177
	v_pk_add_f32 v[178:179], v[178:179], 1.0 op_sel_hi:[1,0]
	s_nop 0
	v_rcp_f32_e32 v178, v178
	v_pk_add_f32 v[176:177], v[176:177], 1.0 op_sel_hi:[1,0]
	v_rcp_f32_e32 v179, v179
	v_rcp_f32_e32 v176, v176
	v_rcp_f32_e32 v177, v177
	v_pk_mul_f32 v[202:203], v[202:203], v[178:179]
	v_pk_mul_f32 v[178:179], v[208:209], v[208:209]
	v_pk_mul_f32 v[204:205], v[204:205], v[176:177]
	v_pk_mul_f32 v[176:177], v[206:207], v[206:207]
	v_pk_fma_f32 v[178:179], v[178:179], s[96:97], v[180:181] op_sel_hi:[1,0,0] neg_lo:[1,0,0] neg_hi:[1,0,0]
	v_pk_fma_f32 v[176:177], v[176:177], s[96:97], v[180:181] op_sel_hi:[1,0,0] neg_lo:[1,0,0] neg_hi:[1,0,0]
	v_pk_mul_f32 v[178:179], v[208:209], v[178:179]
	v_pk_mul_f32 v[176:177], v[206:207], v[176:177]
	v_exp_f32_e32 v178, v178
	v_exp_f32_e32 v179, v179
	v_exp_f32_e32 v176, v176
	v_exp_f32_e32 v177, v177
	v_pk_add_f32 v[178:179], v[178:179], 1.0 op_sel_hi:[1,0]
	s_nop 0
	v_rcp_f32_e32 v178, v178
	v_pk_add_f32 v[176:177], v[176:177], 1.0 op_sel_hi:[1,0]
	v_rcp_f32_e32 v179, v179
	v_rcp_f32_e32 v176, v176
	v_rcp_f32_e32 v177, v177
	v_pk_mul_f32 v[208:209], v[208:209], v[178:179]
	v_pk_mul_f32 v[206:207], v[206:207], v[176:177]
.LBB0_738:
	v_or_b32_e32 v176, 48, v198
	v_ashrrev_i32_e32 v177, 31, v176
	v_lshlrev_b64 v[176:177], 16, v[176:177]
	v_lshl_add_u64 v[176:177], v[146:147], 0, v[176:177]
	s_and_b64 vcc, exec, s[12:13]
	v_cvt_pk_bf16_f32 v178, v202, v203
	v_cvt_pk_bf16_f32 v179, v204, v205
	v_cvt_pk_bf16_f32 v180, v208, v209
	v_cvt_pk_bf16_f32 v181, v206, v207
	global_store_dwordx4 v[176:177], v[178:181], off
	s_cbranch_vccnz .LBB0_740
	global_load_dword v178, v[168:169], off offset:512
	s_waitcnt vmcnt(0)
	s_branch .LBB0_741

.LBB0_741:
	v_pk_fma_f32 v[212:213], v[68:69], v[144:145], v[178:179] op_sel_hi:[1,1,0]
	v_pk_fma_f32 v[210:211], v[66:67], v[162:163], v[178:179] op_sel_hi:[1,1,0]
	v_pk_fma_f32 v[214:215], v[64:65], v[142:143], v[178:179] op_sel_hi:[1,1,0]
	s_and_b64 vcc, exec, s[10:11]
	v_pk_fma_f32 v[216:217], v[62:63], v[158:159], v[178:179] op_sel_hi:[1,1,0]
	s_cbranch_vccnz .LBB0_743
	v_pk_mul_f32 v[178:179], v[212:213], v[212:213]
	v_pk_mul_f32 v[180:181], v[210:211], v[210:211]
	v_mov_b64_e32 v[196:197], s[88:89]
	v_pk_fma_f32 v[180:181], v[180:181], s[96:97], v[196:197] op_sel_hi:[1,0,0] neg_lo:[1,0,0] neg_hi:[1,0,0]
	v_pk_fma_f32 v[178:179], v[178:179], s[96:97], v[196:197] op_sel_hi:[1,0,0] neg_lo:[1,0,0] neg_hi:[1,0,0]
	v_pk_mul_f32 v[180:181], v[210:211], v[180:181]
	v_pk_mul_f32 v[178:179], v[212:213], v[178:179]
	v_exp_f32_e32 v180, v180
	v_exp_f32_e32 v181, v181
	v_exp_f32_e32 v178, v178
	v_exp_f32_e32 v179, v179
	v_pk_add_f32 v[180:181], v[180:181], 1.0 op_sel_hi:[1,0]
	s_nop 0
	v_rcp_f32_e32 v180, v180
	v_pk_add_f32 v[178:179], v[178:179], 1.0 op_sel_hi:[1,0]
	v_rcp_f32_e32 v181, v181
	v_rcp_f32_e32 v178, v178
	v_rcp_f32_e32 v179, v179
	v_pk_mul_f32 v[210:211], v[210:211], v[180:181]
	v_pk_mul_f32 v[180:181], v[216:217], v[216:217]
	v_pk_mul_f32 v[212:213], v[212:213], v[178:179]
	v_pk_mul_f32 v[178:179], v[214:215], v[214:215]
	v_pk_fma_f32 v[180:181], v[180:181], s[96:97], v[196:197] op_sel_hi:[1,0,0] neg_lo:[1,0,0] neg_hi:[1,0,0]
	v_pk_fma_f32 v[178:179], v[178:179], s[96:97], v[196:197] op_sel_hi:[1,0,0] neg_lo:[1,0,0] neg_hi:[1,0,0]
	v_pk_mul_f32 v[180:181], v[216:217], v[180:181]
	v_pk_mul_f32 v[178:179], v[214:215], v[178:179]
	v_exp_f32_e32 v180, v180
	v_exp_f32_e32 v181, v181
	v_exp_f32_e32 v178, v178
	v_exp_f32_e32 v179, v179
	v_pk_add_f32 v[180:181], v[180:181], 1.0 op_sel_hi:[1,0]
	s_nop 0
	v_rcp_f32_e32 v180, v180
	v_pk_add_f32 v[178:179], v[178:179], 1.0 op_sel_hi:[1,0]
	v_rcp_f32_e32 v181, v181
	v_rcp_f32_e32 v178, v178
	v_rcp_f32_e32 v179, v179
	v_pk_mul_f32 v[216:217], v[216:217], v[180:181]
	v_pk_mul_f32 v[214:215], v[214:215], v[178:179]
.LBB0_743:
	v_lshlrev_b64 v[178:179], 16, v[198:199]
	v_lshl_add_u64 v[178:179], v[146:147], 0, v[178:179]
	v_add_co_u32_e32 v180, vcc, 0x800000, v178
	v_cvt_pk_bf16_f32 v218, v210, v211
	v_cvt_pk_bf16_f32 v219, v212, v213
	v_cvt_pk_bf16_f32 v220, v216, v217
	v_cvt_pk_bf16_f32 v221, v214, v215
	s_nop 1
	v_addc_co_u32_e32 v181, vcc, 0, v179, vcc
	s_and_b64 vcc, exec, s[12:13]
	global_store_dwordx4 v[180:181], v[218:221], off
	s_cbranch_vccnz .LBB0_745
	global_load_dword v180, v[168:169], off offset:576
	s_waitcnt vmcnt(0)
	s_branch .LBB0_746

.LBB0_746:
	v_pk_fma_f32 v[220:221], v[52:53], v[144:145], v[180:181] op_sel_hi:[1,1,0]
	v_pk_fma_f32 v[218:219], v[50:51], v[162:163], v[180:181] op_sel_hi:[1,1,0]
	v_pk_fma_f32 v[222:223], v[48:49], v[142:143], v[180:181] op_sel_hi:[1,1,0]
	s_and_b64 vcc, exec, s[10:11]
	v_pk_fma_f32 v[224:225], v[46:47], v[158:159], v[180:181] op_sel_hi:[1,1,0]
	s_cbranch_vccnz .LBB0_748
	v_pk_mul_f32 v[180:181], v[220:221], v[220:221]
	v_pk_mul_f32 v[196:197], v[218:219], v[218:219]
	v_mov_b64_e32 v[226:227], s[88:89]
	v_pk_fma_f32 v[196:197], v[196:197], s[96:97], v[226:227] op_sel_hi:[1,0,0] neg_lo:[1,0,0] neg_hi:[1,0,0]
	v_pk_fma_f32 v[180:181], v[180:181], s[96:97], v[226:227] op_sel_hi:[1,0,0] neg_lo:[1,0,0] neg_hi:[1,0,0]
	v_pk_mul_f32 v[196:197], v[218:219], v[196:197]
	v_pk_mul_f32 v[180:181], v[220:221], v[180:181]
	v_exp_f32_e32 v196, v196
	v_exp_f32_e32 v197, v197
	v_exp_f32_e32 v180, v180
	v_exp_f32_e32 v181, v181
	v_pk_add_f32 v[196:197], v[196:197], 1.0 op_sel_hi:[1,0]
	s_nop 0
	v_rcp_f32_e32 v196, v196
	v_pk_add_f32 v[180:181], v[180:181], 1.0 op_sel_hi:[1,0]
	v_rcp_f32_e32 v197, v197
	v_rcp_f32_e32 v180, v180
	v_rcp_f32_e32 v181, v181
	v_pk_mul_f32 v[218:219], v[218:219], v[196:197]
	v_pk_mul_f32 v[196:197], v[224:225], v[224:225]
	v_pk_mul_f32 v[220:221], v[220:221], v[180:181]
	v_pk_mul_f32 v[180:181], v[222:223], v[222:223]
	v_pk_fma_f32 v[196:197], v[196:197], s[96:97], v[226:227] op_sel_hi:[1,0,0] neg_lo:[1,0,0] neg_hi:[1,0,0]
	v_pk_fma_f32 v[180:181], v[180:181], s[96:97], v[226:227] op_sel_hi:[1,0,0] neg_lo:[1,0,0] neg_hi:[1,0,0]
	v_pk_mul_f32 v[196:197], v[224:225], v[196:197]
	v_pk_mul_f32 v[180:181], v[222:223], v[180:181]
	v_exp_f32_e32 v196, v196
	v_exp_f32_e32 v197, v197
	v_exp_f32_e32 v180, v180
	v_exp_f32_e32 v181, v181
	v_pk_add_f32 v[196:197], v[196:197], 1.0 op_sel_hi:[1,0]
	s_nop 0
	v_rcp_f32_e32 v196, v196
	v_pk_add_f32 v[180:181], v[180:181], 1.0 op_sel_hi:[1,0]
	v_rcp_f32_e32 v197, v197
	v_rcp_f32_e32 v180, v180
	v_rcp_f32_e32 v181, v181
	v_pk_mul_f32 v[224:225], v[224:225], v[196:197]
	v_pk_mul_f32 v[222:223], v[222:223], v[180:181]
.LBB0_748:
	v_lshlrev_b64 v[180:181], 16, v[198:199]
	v_lshl_add_u64 v[180:181], v[146:147], 0, v[180:181]
	v_add_co_u32_e32 v196, vcc, 0x900000, v180
	v_cvt_pk_bf16_f32 v226, v218, v219
	v_cvt_pk_bf16_f32 v227, v220, v221
	v_cvt_pk_bf16_f32 v228, v224, v225
	v_cvt_pk_bf16_f32 v229, v222, v223
	s_nop 1
	v_addc_co_u32_e32 v197, vcc, 0, v181, vcc
	s_and_b64 vcc, exec, s[12:13]
	global_store_dwordx4 v[196:197], v[226:229], off
	s_cbranch_vccnz .LBB0_750
	global_load_dword v196, v[168:169], off offset:640
	s_waitcnt vmcnt(0)
	s_branch .LBB0_751

.LBB0_751:
	v_pk_fma_f32 v[228:229], v[36:37], v[144:145], v[196:197] op_sel_hi:[1,1,0]
	v_pk_fma_f32 v[226:227], v[34:35], v[162:163], v[196:197] op_sel_hi:[1,1,0]
	v_pk_fma_f32 v[230:231], v[32:33], v[142:143], v[196:197] op_sel_hi:[1,1,0]
	s_and_b64 vcc, exec, s[10:11]
	v_pk_fma_f32 v[232:233], v[30:31], v[158:159], v[196:197] op_sel_hi:[1,1,0]
	s_cbranch_vccnz .LBB0_753
	v_pk_mul_f32 v[196:197], v[228:229], v[228:229]
	v_pk_mul_f32 v[234:235], v[226:227], v[226:227]
	v_mov_b64_e32 v[248:249], s[88:89]
	v_pk_fma_f32 v[234:235], v[234:235], s[96:97], v[248:249] op_sel_hi:[1,0,0] neg_lo:[1,0,0] neg_hi:[1,0,0]
	v_pk_fma_f32 v[196:197], v[196:197], s[96:97], v[248:249] op_sel_hi:[1,0,0] neg_lo:[1,0,0] neg_hi:[1,0,0]
	v_pk_mul_f32 v[234:235], v[226:227], v[234:235]
	v_pk_mul_f32 v[196:197], v[228:229], v[196:197]
	v_exp_f32_e32 v234, v234
	v_exp_f32_e32 v235, v235
	v_exp_f32_e32 v196, v196
	v_exp_f32_e32 v197, v197
	v_pk_add_f32 v[234:235], v[234:235], 1.0 op_sel_hi:[1,0]
	s_nop 0
	v_rcp_f32_e32 v234, v234
	v_pk_add_f32 v[196:197], v[196:197], 1.0 op_sel_hi:[1,0]
	v_rcp_f32_e32 v235, v235
	v_rcp_f32_e32 v196, v196
	v_rcp_f32_e32 v197, v197
	v_pk_mul_f32 v[226:227], v[226:227], v[234:235]
	v_pk_mul_f32 v[234:235], v[232:233], v[232:233]
	v_pk_mul_f32 v[228:229], v[228:229], v[196:197]
	v_pk_mul_f32 v[196:197], v[230:231], v[230:231]
	v_pk_fma_f32 v[234:235], v[234:235], s[96:97], v[248:249] op_sel_hi:[1,0,0] neg_lo:[1,0,0] neg_hi:[1,0,0]
	v_pk_fma_f32 v[196:197], v[196:197], s[96:97], v[248:249] op_sel_hi:[1,0,0] neg_lo:[1,0,0] neg_hi:[1,0,0]
	v_pk_mul_f32 v[234:235], v[232:233], v[234:235]
	v_pk_mul_f32 v[196:197], v[230:231], v[196:197]
	v_exp_f32_e32 v234, v234
	v_exp_f32_e32 v235, v235
	v_exp_f32_e32 v196, v196
	v_exp_f32_e32 v197, v197
	v_pk_add_f32 v[234:235], v[234:235], 1.0 op_sel_hi:[1,0]
	s_nop 0
	v_rcp_f32_e32 v234, v234
	v_pk_add_f32 v[196:197], v[196:197], 1.0 op_sel_hi:[1,0]
	v_rcp_f32_e32 v235, v235
	v_rcp_f32_e32 v196, v196
	v_rcp_f32_e32 v197, v197
	v_pk_mul_f32 v[232:233], v[232:233], v[234:235]
	v_pk_mul_f32 v[230:231], v[230:231], v[196:197]
.LBB0_753:
	v_lshlrev_b64 v[196:197], 16, v[198:199]
	v_lshl_add_u64 v[196:197], v[146:147], 0, v[196:197]
	v_add_co_u32_e32 v234, vcc, 0xa00000, v196
	v_cvt_pk_bf16_f32 v248, v226, v227
	v_cvt_pk_bf16_f32 v249, v228, v229
	v_cvt_pk_bf16_f32 v250, v232, v233
	v_cvt_pk_bf16_f32 v251, v230, v231
	s_nop 1
	v_addc_co_u32_e32 v235, vcc, 0, v197, vcc
	s_and_b64 vcc, exec, s[12:13]
	global_store_dwordx4 v[234:235], v[248:251], off
	s_cbranch_vccnz .LBB0_755
	global_load_dword v236, v[168:169], off offset:704
	s_waitcnt vmcnt(0)
	s_branch .LBB0_756

.LBB0_756:
	v_pk_fma_f32 v[234:235], v[20:21], v[144:145], v[236:237] op_sel_hi:[1,1,0]
	v_pk_fma_f32 v[144:145], v[18:19], v[162:163], v[236:237] op_sel_hi:[1,1,0]
	v_pk_fma_f32 v[142:143], v[16:17], v[142:143], v[236:237] op_sel_hi:[1,1,0]
	s_and_b64 vcc, exec, s[10:11]
	v_pk_fma_f32 v[158:159], v[14:15], v[158:159], v[236:237] op_sel_hi:[1,1,0]
	s_cbranch_vccnz .LBB0_758
	v_pk_mul_f32 v[162:163], v[234:235], v[234:235]
	v_pk_mul_f32 v[248:249], v[144:145], v[144:145]
	v_mov_b64_e32 v[250:251], s[88:89]
	v_pk_fma_f32 v[248:249], v[248:249], s[96:97], v[250:251] op_sel_hi:[1,0,0] neg_lo:[1,0,0] neg_hi:[1,0,0]
	v_pk_fma_f32 v[162:163], v[162:163], s[96:97], v[250:251] op_sel_hi:[1,0,0] neg_lo:[1,0,0] neg_hi:[1,0,0]
	v_pk_mul_f32 v[248:249], v[144:145], v[248:249]
	v_pk_mul_f32 v[162:163], v[234:235], v[162:163]
	v_exp_f32_e32 v248, v248
	v_exp_f32_e32 v249, v249
	v_exp_f32_e32 v162, v162
	v_exp_f32_e32 v163, v163
	v_pk_add_f32 v[248:249], v[248:249], 1.0 op_sel_hi:[1,0]
	s_nop 0
	v_rcp_f32_e32 v248, v248
	v_pk_add_f32 v[162:163], v[162:163], 1.0 op_sel_hi:[1,0]
	v_rcp_f32_e32 v249, v249
	v_rcp_f32_e32 v162, v162
	v_rcp_f32_e32 v163, v163
	v_pk_mul_f32 v[144:145], v[144:145], v[248:249]
	v_pk_mul_f32 v[248:249], v[158:159], v[158:159]
	v_pk_mul_f32 v[234:235], v[234:235], v[162:163]
	v_pk_mul_f32 v[162:163], v[142:143], v[142:143]
	v_pk_fma_f32 v[248:249], v[248:249], s[96:97], v[250:251] op_sel_hi:[1,0,0] neg_lo:[1,0,0] neg_hi:[1,0,0]
	v_pk_fma_f32 v[162:163], v[162:163], s[96:97], v[250:251] op_sel_hi:[1,0,0] neg_lo:[1,0,0] neg_hi:[1,0,0]
	v_pk_mul_f32 v[248:249], v[158:159], v[248:249]
	v_pk_mul_f32 v[162:163], v[142:143], v[162:163]
	v_exp_f32_e32 v248, v248
	v_exp_f32_e32 v249, v249
	v_exp_f32_e32 v162, v162
	v_exp_f32_e32 v163, v163
	v_pk_add_f32 v[248:249], v[248:249], 1.0 op_sel_hi:[1,0]
	s_nop 0
	v_rcp_f32_e32 v248, v248
	v_pk_add_f32 v[162:163], v[162:163], 1.0 op_sel_hi:[1,0]
	v_rcp_f32_e32 v249, v249
	v_rcp_f32_e32 v162, v162
	v_rcp_f32_e32 v163, v163
	v_pk_mul_f32 v[158:159], v[158:159], v[248:249]
	v_pk_mul_f32 v[142:143], v[142:143], v[162:163]

.LBB0_767:
	s_and_b64 vcc, exec, s[12:13]
	v_cvt_pk_bf16_f32 v146, v136, v137
	v_cvt_pk_bf16_f32 v147, v134, v135
	v_cvt_pk_bf16_f32 v148, v140, v141
	v_cvt_pk_bf16_f32 v149, v138, v139
	global_store_dwordx4 v[170:171], v[146:149], off offset:256
	s_cbranch_vccnz .LBB0_769
	global_load_dword v152, v[168:169], off offset:64
	s_waitcnt vmcnt(0)
	s_branch .LBB0_770

.LBB0_770:
	v_pk_fma_f32 v[148:149], v[108:109], v[144:145], v[152:153] op_sel_hi:[1,1,0]
	v_pk_fma_f32 v[146:147], v[106:107], v[162:163], v[152:153] op_sel_hi:[1,1,0]
	v_pk_fma_f32 v[150:151], v[104:105], v[142:143], v[152:153] op_sel_hi:[1,1,0]
	s_and_b64 vcc, exec, s[10:11]
	v_pk_fma_f32 v[152:153], v[102:103], v[158:159], v[152:153] op_sel_hi:[1,1,0]
	s_cbranch_vccnz .LBB0_772
	v_pk_mul_f32 v[154:155], v[148:149], v[148:149]
	v_pk_mul_f32 v[156:157], v[146:147], v[146:147]
	v_mov_b64_e32 v[160:161], s[88:89]
	v_pk_fma_f32 v[156:157], v[156:157], s[96:97], v[160:161] op_sel_hi:[1,0,0] neg_lo:[1,0,0] neg_hi:[1,0,0]
	v_pk_fma_f32 v[154:155], v[154:155], s[96:97], v[160:161] op_sel_hi:[1,0,0] neg_lo:[1,0,0] neg_hi:[1,0,0]
	v_pk_mul_f32 v[156:157], v[146:147], v[156:157]
	v_pk_mul_f32 v[154:155], v[148:149], v[154:155]
	v_exp_f32_e32 v156, v156
	v_exp_f32_e32 v157, v157
	v_exp_f32_e32 v154, v154
	v_exp_f32_e32 v155, v155
	v_pk_add_f32 v[156:157], v[156:157], 1.0 op_sel_hi:[1,0]
	s_nop 0
	v_rcp_f32_e32 v156, v156
	v_pk_add_f32 v[154:155], v[154:155], 1.0 op_sel_hi:[1,0]
	v_rcp_f32_e32 v157, v157
	v_rcp_f32_e32 v154, v154
	v_rcp_f32_e32 v155, v155
	v_pk_mul_f32 v[146:147], v[146:147], v[156:157]
	v_pk_mul_f32 v[156:157], v[152:153], v[152:153]
	v_pk_mul_f32 v[148:149], v[148:149], v[154:155]
	v_pk_mul_f32 v[154:155], v[150:151], v[150:151]
	v_pk_fma_f32 v[156:157], v[156:157], s[96:97], v[160:161] op_sel_hi:[1,0,0] neg_lo:[1,0,0] neg_hi:[1,0,0]
	v_pk_fma_f32 v[154:155], v[154:155], s[96:97], v[160:161] op_sel_hi:[1,0,0] neg_lo:[1,0,0] neg_hi:[1,0,0]
	v_pk_mul_f32 v[156:157], v[152:153], v[156:157]
	v_pk_mul_f32 v[154:155], v[150:151], v[154:155]
	v_exp_f32_e32 v156, v156
	v_exp_f32_e32 v157, v157
	v_exp_f32_e32 v154, v154
	v_exp_f32_e32 v155, v155
	v_pk_add_f32 v[156:157], v[156:157], 1.0 op_sel_hi:[1,0]
	s_nop 0
	v_rcp_f32_e32 v156, v156
	v_pk_add_f32 v[154:155], v[154:155], 1.0 op_sel_hi:[1,0]
	v_rcp_f32_e32 v157, v157
	v_rcp_f32_e32 v154, v154
	v_rcp_f32_e32 v155, v155
	v_pk_mul_f32 v[152:153], v[152:153], v[156:157]
	v_pk_mul_f32 v[150:151], v[150:151], v[154:155]
.LBB0_772:
	s_and_b64 vcc, exec, s[12:13]
	v_cvt_pk_bf16_f32 v154, v146, v147
	v_cvt_pk_bf16_f32 v155, v148, v149
	v_cvt_pk_bf16_f32 v156, v152, v153
	v_cvt_pk_bf16_f32 v157, v150, v151
	global_store_dwordx4 v[172:173], v[154:157], off offset:256
	s_cbranch_vccnz .LBB0_774
	global_load_dword v164, v[168:169], off offset:128
	s_waitcnt vmcnt(0)
	s_branch .LBB0_775

.LBB0_775:
	v_pk_fma_f32 v[156:157], v[92:93], v[144:145], v[164:165] op_sel_hi:[1,1,0]
	v_pk_fma_f32 v[154:155], v[90:91], v[162:163], v[164:165] op_sel_hi:[1,1,0]
	v_pk_fma_f32 v[160:161], v[88:89], v[142:143], v[164:165] op_sel_hi:[1,1,0]
	s_and_b64 vcc, exec, s[10:11]
	v_pk_fma_f32 v[164:165], v[86:87], v[158:159], v[164:165] op_sel_hi:[1,1,0]
	s_cbranch_vccnz .LBB0_777
	v_pk_mul_f32 v[170:171], v[156:157], v[156:157]
	v_pk_mul_f32 v[172:173], v[154:155], v[154:155]
	v_mov_b64_e32 v[200:201], s[88:89]
	v_pk_fma_f32 v[172:173], v[172:173], s[96:97], v[200:201] op_sel_hi:[1,0,0] neg_lo:[1,0,0] neg_hi:[1,0,0]
	v_pk_fma_f32 v[170:171], v[170:171], s[96:97], v[200:201] op_sel_hi:[1,0,0] neg_lo:[1,0,0] neg_hi:[1,0,0]
	v_pk_mul_f32 v[172:173], v[154:155], v[172:173]
	v_pk_mul_f32 v[170:171], v[156:157], v[170:171]
	v_exp_f32_e32 v172, v172
	v_exp_f32_e32 v173, v173
	v_exp_f32_e32 v170, v170
	v_exp_f32_e32 v171, v171
	v_pk_add_f32 v[172:173], v[172:173], 1.0 op_sel_hi:[1,0]
	s_nop 0
	v_rcp_f32_e32 v172, v172
	v_pk_add_f32 v[170:171], v[170:171], 1.0 op_sel_hi:[1,0]
	v_rcp_f32_e32 v173, v173
	v_rcp_f32_e32 v170, v170
	v_rcp_f32_e32 v171, v171
	v_pk_mul_f32 v[154:155], v[154:155], v[172:173]
	v_pk_mul_f32 v[172:173], v[164:165], v[164:165]
	v_pk_mul_f32 v[156:157], v[156:157], v[170:171]
	v_pk_mul_f32 v[170:171], v[160:161], v[160:161]
	v_pk_fma_f32 v[172:173], v[172:173], s[96:97], v[200:201] op_sel_hi:[1,0,0] neg_lo:[1,0,0] neg_hi:[1,0,0]
	v_pk_fma_f32 v[170:171], v[170:171], s[96:97], v[200:201] op_sel_hi:[1,0,0] neg_lo:[1,0,0] neg_hi:[1,0,0]
	v_pk_mul_f32 v[172:173], v[164:165], v[172:173]
	v_pk_mul_f32 v[170:171], v[160:161], v[170:171]
	v_exp_f32_e32 v172, v172
	v_exp_f32_e32 v173, v173
	v_exp_f32_e32 v170, v170
	v_exp_f32_e32 v171, v171
	v_pk_add_f32 v[172:173], v[172:173], 1.0 op_sel_hi:[1,0]
	s_nop 0
	v_rcp_f32_e32 v172, v172
	v_pk_add_f32 v[170:171], v[170:171], 1.0 op_sel_hi:[1,0]
	v_rcp_f32_e32 v173, v173
	v_rcp_f32_e32 v170, v170
	v_rcp_f32_e32 v171, v171
	v_pk_mul_f32 v[164:165], v[164:165], v[172:173]
	v_pk_mul_f32 v[160:161], v[160:161], v[170:171]
.LBB0_777:
	s_and_b64 vcc, exec, s[12:13]
	v_cvt_pk_bf16_f32 v170, v154, v155
	v_cvt_pk_bf16_f32 v171, v156, v157
	v_cvt_pk_bf16_f32 v172, v164, v165
	v_cvt_pk_bf16_f32 v173, v160, v161
	global_store_dwordx4 v[174:175], v[170:173], off offset:256
	s_cbranch_vccnz .LBB0_779
	global_load_dword v200, v[168:169], off offset:192
	s_waitcnt vmcnt(0)
	s_branch .LBB0_780

.LBB0_780:
	v_pk_fma_f32 v[172:173], v[76:77], v[144:145], v[200:201] op_sel_hi:[1,1,0]
	v_pk_fma_f32 v[170:171], v[74:75], v[162:163], v[200:201] op_sel_hi:[1,1,0]
	v_pk_fma_f32 v[174:175], v[72:73], v[142:143], v[200:201] op_sel_hi:[1,1,0]
	s_and_b64 vcc, exec, s[10:11]
	v_pk_fma_f32 v[200:201], v[70:71], v[158:159], v[200:201] op_sel_hi:[1,1,0]
	s_cbranch_vccnz .LBB0_782
	v_pk_mul_f32 v[202:203], v[172:173], v[172:173]
	v_pk_mul_f32 v[204:205], v[170:171], v[170:171]
	v_mov_b64_e32 v[206:207], s[88:89]
	v_pk_fma_f32 v[204:205], v[204:205], s[96:97], v[206:207] op_sel_hi:[1,0,0] neg_lo:[1,0,0] neg_hi:[1,0,0]
	v_pk_fma_f32 v[202:203], v[202:203], s[96:97], v[206:207] op_sel_hi:[1,0,0] neg_lo:[1,0,0] neg_hi:[1,0,0]
	v_pk_mul_f32 v[204:205], v[170:171], v[204:205]
	v_pk_mul_f32 v[202:203], v[172:173], v[202:203]
	v_exp_f32_e32 v204, v204
	v_exp_f32_e32 v205, v205
	v_exp_f32_e32 v202, v202
	v_exp_f32_e32 v203, v203
	v_pk_add_f32 v[204:205], v[204:205], 1.0 op_sel_hi:[1,0]
	s_nop 0
	v_rcp_f32_e32 v204, v204
	v_pk_add_f32 v[202:203], v[202:203], 1.0 op_sel_hi:[1,0]
	v_rcp_f32_e32 v205, v205
	v_rcp_f32_e32 v202, v202
	v_rcp_f32_e32 v203, v203
	v_pk_mul_f32 v[170:171], v[170:171], v[204:205]
	v_pk_mul_f32 v[204:205], v[200:201], v[200:201]
	v_pk_mul_f32 v[172:173], v[172:173], v[202:203]
	v_pk_mul_f32 v[202:203], v[174:175], v[174:175]
	v_pk_fma_f32 v[204:205], v[204:205], s[96:97], v[206:207] op_sel_hi:[1,0,0] neg_lo:[1,0,0] neg_hi:[1,0,0]
	v_pk_fma_f32 v[202:203], v[202:203], s[96:97], v[206:207] op_sel_hi:[1,0,0] neg_lo:[1,0,0] neg_hi:[1,0,0]
	v_pk_mul_f32 v[204:205], v[200:201], v[204:205]
	v_pk_mul_f32 v[202:203], v[174:175], v[202:203]
	v_exp_f32_e32 v204, v204
	v_exp_f32_e32 v205, v205
	v_exp_f32_e32 v202, v202
	v_exp_f32_e32 v203, v203
	v_pk_add_f32 v[204:205], v[204:205], 1.0 op_sel_hi:[1,0]
	s_nop 0
	v_rcp_f32_e32 v204, v204
	v_pk_add_f32 v[202:203], v[202:203], 1.0 op_sel_hi:[1,0]
	v_rcp_f32_e32 v205, v205
	v_rcp_f32_e32 v202, v202
	v_rcp_f32_e32 v203, v203
	v_pk_mul_f32 v[200:201], v[200:201], v[204:205]
	v_pk_mul_f32 v[174:175], v[174:175], v[202:203]
.LBB0_782:
	s_and_b64 vcc, exec, s[12:13]
	v_cvt_pk_bf16_f32 v202, v170, v171
	v_cvt_pk_bf16_f32 v203, v172, v173
	v_cvt_pk_bf16_f32 v204, v200, v201
	v_cvt_pk_bf16_f32 v205, v174, v175
	global_store_dwordx4 v[176:177], v[202:205], off offset:256
	s_cbranch_vccnz .LBB0_784
	global_load_dword v206, v[168:169], off offset:512
	s_waitcnt vmcnt(0)
	s_branch .LBB0_785

.LBB0_785:
	v_pk_fma_f32 v[202:203], v[60:61], v[144:145], v[206:207] op_sel_hi:[1,1,0]
	v_pk_fma_f32 v[176:177], v[58:59], v[162:163], v[206:207] op_sel_hi:[1,1,0]
	v_pk_fma_f32 v[204:205], v[56:57], v[142:143], v[206:207] op_sel_hi:[1,1,0]
	s_and_b64 vcc, exec, s[10:11]
	v_pk_fma_f32 v[206:207], v[54:55], v[158:159], v[206:207] op_sel_hi:[1,1,0]
	s_cbranch_vccnz .LBB0_787
	v_pk_mul_f32 v[208:209], v[202:203], v[202:203]
	v_pk_mul_f32 v[210:211], v[176:177], v[176:177]
	v_mov_b64_e32 v[212:213], s[88:89]
	v_pk_fma_f32 v[210:211], v[210:211], s[96:97], v[212:213] op_sel_hi:[1,0,0] neg_lo:[1,0,0] neg_hi:[1,0,0]
	v_pk_fma_f32 v[208:209], v[208:209], s[96:97], v[212:213] op_sel_hi:[1,0,0] neg_lo:[1,0,0] neg_hi:[1,0,0]
	v_pk_mul_f32 v[210:211], v[176:177], v[210:211]
	v_pk_mul_f32 v[208:209], v[202:203], v[208:209]
	v_exp_f32_e32 v210, v210
	v_exp_f32_e32 v211, v211
	v_exp_f32_e32 v208, v208
	v_exp_f32_e32 v209, v209
	v_pk_add_f32 v[210:211], v[210:211], 1.0 op_sel_hi:[1,0]
	s_nop 0
	v_rcp_f32_e32 v210, v210
	v_pk_add_f32 v[208:209], v[208:209], 1.0 op_sel_hi:[1,0]
	v_rcp_f32_e32 v211, v211
	v_rcp_f32_e32 v208, v208
	v_rcp_f32_e32 v209, v209
	v_pk_mul_f32 v[176:177], v[176:177], v[210:211]
	v_pk_mul_f32 v[210:211], v[206:207], v[206:207]
	v_pk_mul_f32 v[202:203], v[202:203], v[208:209]
	v_pk_mul_f32 v[208:209], v[204:205], v[204:205]
	v_pk_fma_f32 v[210:211], v[210:211], s[96:97], v[212:213] op_sel_hi:[1,0,0] neg_lo:[1,0,0] neg_hi:[1,0,0]
	v_pk_fma_f32 v[208:209], v[208:209], s[96:97], v[212:213] op_sel_hi:[1,0,0] neg_lo:[1,0,0] neg_hi:[1,0,0]
	v_pk_mul_f32 v[210:211], v[206:207], v[210:211]
	v_pk_mul_f32 v[208:209], v[204:205], v[208:209]
	v_exp_f32_e32 v210, v210
	v_exp_f32_e32 v211, v211
	v_exp_f32_e32 v208, v208
	v_exp_f32_e32 v209, v209
	v_pk_add_f32 v[210:211], v[210:211], 1.0 op_sel_hi:[1,0]
	s_nop 0
	v_rcp_f32_e32 v210, v210
	v_pk_add_f32 v[208:209], v[208:209], 1.0 op_sel_hi:[1,0]
	v_rcp_f32_e32 v211, v211
	v_rcp_f32_e32 v208, v208
	v_rcp_f32_e32 v209, v209
	v_pk_mul_f32 v[206:207], v[206:207], v[210:211]
	v_pk_mul_f32 v[204:205], v[204:205], v[208:209]
.LBB0_787:
	s_mov_b64 s[26:27], 0x800000
	v_lshl_add_u64 v[178:179], v[178:179], 0, s[26:27]
	s_and_b64 vcc, exec, s[12:13]
	v_cvt_pk_bf16_f32 v208, v176, v177
	v_cvt_pk_bf16_f32 v209, v202, v203
	v_cvt_pk_bf16_f32 v210, v206, v207
	v_cvt_pk_bf16_f32 v211, v204, v205
	global_store_dwordx4 v[178:179], v[208:211], off offset:256
	s_cbranch_vccnz .LBB0_789
	global_load_dword v212, v[168:169], off offset:576
	s_waitcnt vmcnt(0)
	s_branch .LBB0_790

.LBB0_790:
	v_pk_fma_f32 v[208:209], v[44:45], v[144:145], v[212:213] op_sel_hi:[1,1,0]
	v_pk_fma_f32 v[178:179], v[42:43], v[162:163], v[212:213] op_sel_hi:[1,1,0]
	v_pk_fma_f32 v[210:211], v[40:41], v[142:143], v[212:213] op_sel_hi:[1,1,0]
	s_and_b64 vcc, exec, s[10:11]
	v_pk_fma_f32 v[212:213], v[38:39], v[158:159], v[212:213] op_sel_hi:[1,1,0]
	s_cbranch_vccnz .LBB0_792
	v_pk_mul_f32 v[214:215], v[208:209], v[208:209]
	v_pk_mul_f32 v[216:217], v[178:179], v[178:179]
	v_mov_b64_e32 v[218:219], s[88:89]
	v_pk_fma_f32 v[216:217], v[216:217], s[96:97], v[218:219] op_sel_hi:[1,0,0] neg_lo:[1,0,0] neg_hi:[1,0,0]
	v_pk_fma_f32 v[214:215], v[214:215], s[96:97], v[218:219] op_sel_hi:[1,0,0] neg_lo:[1,0,0] neg_hi:[1,0,0]
	v_pk_mul_f32 v[216:217], v[178:179], v[216:217]
	v_pk_mul_f32 v[214:215], v[208:209], v[214:215]
	v_exp_f32_e32 v216, v216
	v_exp_f32_e32 v217, v217
	v_exp_f32_e32 v214, v214
	v_exp_f32_e32 v215, v215
	v_pk_add_f32 v[216:217], v[216:217], 1.0 op_sel_hi:[1,0]
	s_nop 0
	v_rcp_f32_e32 v216, v216
	v_pk_add_f32 v[214:215], v[214:215], 1.0 op_sel_hi:[1,0]
	v_rcp_f32_e32 v217, v217
	v_rcp_f32_e32 v214, v214
	v_rcp_f32_e32 v215, v215
	v_pk_mul_f32 v[178:179], v[178:179], v[216:217]
	v_pk_mul_f32 v[216:217], v[212:213], v[212:213]
	v_pk_mul_f32 v[208:209], v[208:209], v[214:215]
	v_pk_mul_f32 v[214:215], v[210:211], v[210:211]
	v_pk_fma_f32 v[216:217], v[216:217], s[96:97], v[218:219] op_sel_hi:[1,0,0] neg_lo:[1,0,0] neg_hi:[1,0,0]
	v_pk_fma_f32 v[214:215], v[214:215], s[96:97], v[218:219] op_sel_hi:[1,0,0] neg_lo:[1,0,0] neg_hi:[1,0,0]
	v_pk_mul_f32 v[216:217], v[212:213], v[216:217]
	v_pk_mul_f32 v[214:215], v[210:211], v[214:215]
	v_exp_f32_e32 v216, v216
	v_exp_f32_e32 v217, v217
	v_exp_f32_e32 v214, v214
	v_exp_f32_e32 v215, v215
	v_pk_add_f32 v[216:217], v[216:217], 1.0 op_sel_hi:[1,0]
	s_nop 0
	v_rcp_f32_e32 v216, v216
	v_pk_add_f32 v[214:215], v[214:215], 1.0 op_sel_hi:[1,0]
	v_rcp_f32_e32 v217, v217
	v_rcp_f32_e32 v214, v214
	v_rcp_f32_e32 v215, v215
	v_pk_mul_f32 v[212:213], v[212:213], v[216:217]
	v_pk_mul_f32 v[210:211], v[210:211], v[214:215]
.LBB0_792:
	s_mov_b64 s[26:27], 0x900000
	v_lshl_add_u64 v[180:181], v[180:181], 0, s[26:27]
	s_and_b64 vcc, exec, s[12:13]
	v_cvt_pk_bf16_f32 v214, v178, v179
	v_cvt_pk_bf16_f32 v215, v208, v209
	v_cvt_pk_bf16_f32 v216, v212, v213
	v_cvt_pk_bf16_f32 v217, v210, v211
	global_store_dwordx4 v[180:181], v[214:217], off offset:256
	s_cbranch_vccnz .LBB0_794
	global_load_dword v218, v[168:169], off offset:640
	s_waitcnt vmcnt(0)
	s_branch .LBB0_795

.LBB0_795:
	v_pk_fma_f32 v[214:215], v[28:29], v[144:145], v[218:219] op_sel_hi:[1,1,0]
	v_pk_fma_f32 v[180:181], v[26:27], v[162:163], v[218:219] op_sel_hi:[1,1,0]
	v_pk_fma_f32 v[216:217], v[24:25], v[142:143], v[218:219] op_sel_hi:[1,1,0]
	s_and_b64 vcc, exec, s[10:11]
	v_pk_fma_f32 v[218:219], v[22:23], v[158:159], v[218:219] op_sel_hi:[1,1,0]
	s_cbranch_vccnz .LBB0_797
	v_pk_mul_f32 v[220:221], v[214:215], v[214:215]
	v_pk_mul_f32 v[222:223], v[180:181], v[180:181]
	v_mov_b64_e32 v[224:225], s[88:89]
	v_pk_fma_f32 v[222:223], v[222:223], s[96:97], v[224:225] op_sel_hi:[1,0,0] neg_lo:[1,0,0] neg_hi:[1,0,0]
	v_pk_fma_f32 v[220:221], v[220:221], s[96:97], v[224:225] op_sel_hi:[1,0,0] neg_lo:[1,0,0] neg_hi:[1,0,0]
	v_pk_mul_f32 v[222:223], v[180:181], v[222:223]
	v_pk_mul_f32 v[220:221], v[214:215], v[220:221]
	v_exp_f32_e32 v222, v222
	v_exp_f32_e32 v223, v223
	v_exp_f32_e32 v220, v220
	v_exp_f32_e32 v221, v221
	v_pk_add_f32 v[222:223], v[222:223], 1.0 op_sel_hi:[1,0]
	s_nop 0
	v_rcp_f32_e32 v222, v222
	v_pk_add_f32 v[220:221], v[220:221], 1.0 op_sel_hi:[1,0]
	v_rcp_f32_e32 v223, v223
	v_rcp_f32_e32 v220, v220
	v_rcp_f32_e32 v221, v221
	v_pk_mul_f32 v[180:181], v[180:181], v[222:223]
	v_pk_mul_f32 v[222:223], v[218:219], v[218:219]
	v_pk_mul_f32 v[214:215], v[214:215], v[220:221]
	v_pk_mul_f32 v[220:221], v[216:217], v[216:217]
	v_pk_fma_f32 v[222:223], v[222:223], s[96:97], v[224:225] op_sel_hi:[1,0,0] neg_lo:[1,0,0] neg_hi:[1,0,0]
	v_pk_fma_f32 v[220:221], v[220:221], s[96:97], v[224:225] op_sel_hi:[1,0,0] neg_lo:[1,0,0] neg_hi:[1,0,0]
	v_pk_mul_f32 v[222:223], v[218:219], v[222:223]
	v_pk_mul_f32 v[220:221], v[216:217], v[220:221]
	v_exp_f32_e32 v222, v222
	v_exp_f32_e32 v223, v223
	v_exp_f32_e32 v220, v220
	v_exp_f32_e32 v221, v221
	v_pk_add_f32 v[222:223], v[222:223], 1.0 op_sel_hi:[1,0]
	s_nop 0
	v_rcp_f32_e32 v222, v222
	v_pk_add_f32 v[220:221], v[220:221], 1.0 op_sel_hi:[1,0]
	v_rcp_f32_e32 v223, v223
	v_rcp_f32_e32 v220, v220
	v_rcp_f32_e32 v221, v221
	v_pk_mul_f32 v[218:219], v[218:219], v[222:223]
	v_pk_mul_f32 v[216:217], v[216:217], v[220:221]
.LBB0_797:
	s_mov_b64 s[26:27], 0xa00000
	v_lshl_add_u64 v[196:197], v[196:197], 0, s[26:27]
	s_and_b64 vcc, exec, s[12:13]
	v_cvt_pk_bf16_f32 v220, v180, v181
	v_cvt_pk_bf16_f32 v221, v214, v215
	v_cvt_pk_bf16_f32 v222, v218, v219
	v_cvt_pk_bf16_f32 v223, v216, v217
	global_store_dwordx4 v[196:197], v[220:223], off offset:256
	s_cbranch_vccnz .LBB0_799
	global_load_dword v196, v[168:169], off offset:704
	s_waitcnt vmcnt(0)
	s_branch .LBB0_800

.LBB0_800:
	v_pk_fma_f32 v[168:169], v[12:13], v[144:145], v[196:197] op_sel_hi:[1,1,0]
	v_pk_fma_f32 v[144:145], v[10:11], v[162:163], v[196:197] op_sel_hi:[1,1,0]
	v_pk_fma_f32 v[142:143], v[8:9], v[142:143], v[196:197] op_sel_hi:[1,1,0]
	s_and_b64 vcc, exec, s[10:11]
	v_pk_fma_f32 v[158:159], v[6:7], v[158:159], v[196:197] op_sel_hi:[1,1,0]
	s_cbranch_vccnz .LBB0_802
	v_pk_mul_f32 v[162:163], v[168:169], v[168:169]
	v_pk_mul_f32 v[196:197], v[144:145], v[144:145]
	v_mov_b64_e32 v[220:221], s[88:89]
	v_pk_fma_f32 v[196:197], v[196:197], s[96:97], v[220:221] op_sel_hi:[1,0,0] neg_lo:[1,0,0] neg_hi:[1,0,0]
	v_pk_fma_f32 v[162:163], v[162:163], s[96:97], v[220:221] op_sel_hi:[1,0,0] neg_lo:[1,0,0] neg_hi:[1,0,0]
	v_pk_mul_f32 v[196:197], v[144:145], v[196:197]
	v_pk_mul_f32 v[162:163], v[168:169], v[162:163]
	v_exp_f32_e32 v196, v196
	v_exp_f32_e32 v197, v197
	v_exp_f32_e32 v162, v162
	v_exp_f32_e32 v163, v163
	v_pk_add_f32 v[196:197], v[196:197], 1.0 op_sel_hi:[1,0]
	s_nop 0
	v_rcp_f32_e32 v196, v196
	v_pk_add_f32 v[162:163], v[162:163], 1.0 op_sel_hi:[1,0]
	v_rcp_f32_e32 v197, v197
	v_rcp_f32_e32 v162, v162
	v_rcp_f32_e32 v163, v163
	v_pk_mul_f32 v[144:145], v[144:145], v[196:197]
	v_pk_mul_f32 v[196:197], v[158:159], v[158:159]
	v_pk_mul_f32 v[168:169], v[168:169], v[162:163]
	v_pk_mul_f32 v[162:163], v[142:143], v[142:143]
	v_pk_fma_f32 v[196:197], v[196:197], s[96:97], v[220:221] op_sel_hi:[1,0,0] neg_lo:[1,0,0] neg_hi:[1,0,0]
	v_pk_fma_f32 v[162:163], v[162:163], s[96:97], v[220:221] op_sel_hi:[1,0,0] neg_lo:[1,0,0] neg_hi:[1,0,0]
	v_pk_mul_f32 v[196:197], v[158:159], v[196:197]
	v_pk_mul_f32 v[162:163], v[142:143], v[162:163]
	v_exp_f32_e32 v196, v196
	v_exp_f32_e32 v197, v197
	v_exp_f32_e32 v162, v162
	v_exp_f32_e32 v163, v163
	v_pk_add_f32 v[196:197], v[196:197], 1.0 op_sel_hi:[1,0]
	s_nop 0
	v_rcp_f32_e32 v196, v196
	v_pk_add_f32 v[162:163], v[162:163], 1.0 op_sel_hi:[1,0]
	v_rcp_f32_e32 v197, v197
	v_rcp_f32_e32 v162, v162
	v_rcp_f32_e32 v163, v163
	v_pk_mul_f32 v[158:159], v[158:159], v[196:197]
	v_pk_mul_f32 v[142:143], v[142:143], v[162:163]

.LBB0_1065:
	s_add_i32 s44, s26, 2
	s_add_u32 s45, s10, 0x80
	s_addc_u32 s27, s11, 0
	s_add_i32 s72, 0, 0x10000
	s_cmp_eq_u32 s68, s26
	s_cselect_b32 s27, s25, s27
	s_cselect_b32 s26, s24, s45
	s_cselect_b32 s71, s29, s31
	s_cselect_b32 s70, s28, s30
	s_add_i32 s45, 0, 0x14000
	v_add_u32_e32 v114, s72, v217
	v_add_u32_e32 v162, s45, v217
	ds_read_b128 v[94:97], v114
	ds_read_b128 v[102:105], v114 offset:1024
	ds_read_b128 v[110:113], v114 offset:2048
	ds_read_b128 v[114:117], v114 offset:3072
	ds_read_b128 v[150:153], v162
	ds_read_b128 v[154:157], v162 offset:1024
	ds_read_b128 v[158:161], v162 offset:2048
	ds_read_b128 v[162:165], v162 offset:3072
	s_add_i32 m0, s57, 0xc000
	ds_read_b128 v[166:169], v236
	ds_read_b128 v[170:173], v236 offset:1024
	ds_read_b128 v[174:177], v236 offset:2048
	ds_read_b128 v[178:181], v236 offset:3072
	ds_read_b128 v[196:199], v236 offset:4096
	ds_read_b128 v[200:203], v236 offset:5120
	ds_read_b128 v[204:207], v236 offset:6144
	ds_read_b128 v[208:211], v236 offset:7168
	global_load_lds_dwordx4 v192, s[10:11]
	s_add_i32 m0, s57, 0xe000
	s_nop 0
	global_load_lds_dwordx4 v194, s[10:11]
	s_waitcnt vmcnt(8)
	s_waitcnt lgkmcnt(0)
	s_barrier
	s_setprio 1
	s_waitcnt lgkmcnt(0)
	v_mfma_f32_16x16x32_bf16 v[146:149], v[94:97], v[166:169], v[146:149]
	v_mfma_f32_16x16x32_bf16 v[142:145], v[110:113], v[166:169], v[142:145]
	v_mfma_f32_16x16x32_bf16 v[130:133], v[94:97], v[174:177], v[130:133]
	v_mfma_f32_16x16x32_bf16 v[126:129], v[110:113], v[174:177], v[126:129]
	v_mfma_f32_16x16x32_bf16 v[106:109], v[94:97], v[196:199], v[106:109]
	v_mfma_f32_16x16x32_bf16 v[98:101], v[110:113], v[196:199], v[98:101]
	v_mfma_f32_16x16x32_bf16 v[82:85], v[94:97], v[204:207], v[82:85]
	v_mfma_f32_16x16x32_bf16 v[78:81], v[110:113], v[204:207], v[78:81]
	v_mfma_f32_16x16x32_bf16 v[146:149], v[102:105], v[170:173], v[146:149]
	v_mfma_f32_16x16x32_bf16 v[142:145], v[114:117], v[170:173], v[142:145]
	v_mfma_f32_16x16x32_bf16 v[130:133], v[102:105], v[178:181], v[130:133]
	v_mfma_f32_16x16x32_bf16 v[126:129], v[114:117], v[178:181], v[126:129]
	v_mfma_f32_16x16x32_bf16 v[106:109], v[102:105], v[200:203], v[106:109]
	v_mfma_f32_16x16x32_bf16 v[98:101], v[114:117], v[200:203], v[98:101]
	v_mfma_f32_16x16x32_bf16 v[82:85], v[102:105], v[208:211], v[82:85]
	v_mfma_f32_16x16x32_bf16 v[78:81], v[114:117], v[208:211], v[78:81]
	s_setprio 0
	s_setprio 1
	v_mfma_f32_16x16x32_bf16 v[138:141], v[150:153], v[166:169], v[138:141]
	v_mfma_f32_16x16x32_bf16 v[134:137], v[158:161], v[166:169], v[134:137]
	v_mfma_f32_16x16x32_bf16 v[122:125], v[150:153], v[174:177], v[122:125]
	v_mfma_f32_16x16x32_bf16 v[118:121], v[158:161], v[174:177], v[118:121]
	v_mfma_f32_16x16x32_bf16 v[90:93], v[150:153], v[196:199], v[90:93]
	v_mfma_f32_16x16x32_bf16 v[86:89], v[158:161], v[196:199], v[86:89]
	v_mfma_f32_16x16x32_bf16 v[74:77], v[150:153], v[204:207], v[74:77]
	v_mfma_f32_16x16x32_bf16 v[70:73], v[158:161], v[204:207], v[70:73]
	v_mfma_f32_16x16x32_bf16 v[138:141], v[154:157], v[170:173], v[138:141]
	v_mfma_f32_16x16x32_bf16 v[134:137], v[162:165], v[170:173], v[134:137]
	v_mfma_f32_16x16x32_bf16 v[122:125], v[154:157], v[178:181], v[122:125]
	v_mfma_f32_16x16x32_bf16 v[118:121], v[162:165], v[178:181], v[118:121]
	v_mfma_f32_16x16x32_bf16 v[90:93], v[154:157], v[200:203], v[90:93]
	v_mfma_f32_16x16x32_bf16 v[86:89], v[162:165], v[200:203], v[86:89]
	v_mfma_f32_16x16x32_bf16 v[74:77], v[154:157], v[208:211], v[74:77]
	v_mfma_f32_16x16x32_bf16 v[70:73], v[162:165], v[208:211], v[70:73]
	s_setprio 0
	s_barrier
	s_add_i32 s72, s72, s54
	s_mov_b32 m0, s72
	ds_read_b128 v[166:169], v236 offset:16384
	ds_read_b128 v[170:173], v236 offset:17408
	ds_read_b128 v[174:177], v236 offset:18432
	ds_read_b128 v[178:181], v236 offset:19456
	ds_read_b128 v[196:199], v236 offset:20480
	ds_read_b128 v[200:203], v236 offset:21504
	ds_read_b128 v[204:207], v236 offset:22528
	ds_read_b128 v[208:211], v236 offset:23552
	global_load_lds_dwordx4 v0, s[70:71]
	s_add_i32 m0, s72, 0x2000
	s_add_u32 s100, s70, 0x80
	s_addc_u32 s101, s71, 0
	global_load_lds_dwordx4 v190, s[70:71]
	s_add_u32 s70, s70, s42
	s_addc_u32 s71, s71, 0
	s_add_i32 s45, s45, s54
	s_mov_b32 m0, s45
	s_nop 0
	global_load_lds_dwordx4 v0, s[70:71]
	s_add_i32 m0, s45, 0x2000
	s_nop 0
	global_load_lds_dwordx4 v190, s[70:71]
	s_mov_b32 m0, s57
	s_nop 0
	global_load_lds_dwordx4 v182, s[26:27]
	s_mov_b32 m0, s58
	s_nop 0
	global_load_lds_dwordx4 v188, s[26:27]
	s_waitcnt vmcnt(8)
	s_waitcnt lgkmcnt(0)
	s_barrier
	s_setprio 1
	s_waitcnt lgkmcnt(0)
	v_mfma_f32_16x16x32_bf16 v[66:69], v[94:97], v[166:169], v[66:69]
	v_mfma_f32_16x16x32_bf16 v[62:65], v[110:113], v[166:169], v[62:65]
	v_mfma_f32_16x16x32_bf16 v[50:53], v[94:97], v[174:177], v[50:53]
	v_mfma_f32_16x16x32_bf16 v[46:49], v[110:113], v[174:177], v[46:49]
	v_mfma_f32_16x16x32_bf16 v[34:37], v[94:97], v[196:199], v[34:37]
	v_mfma_f32_16x16x32_bf16 v[30:33], v[110:113], v[196:199], v[30:33]
	v_mfma_f32_16x16x32_bf16 v[18:21], v[94:97], v[204:207], v[18:21]
	v_mfma_f32_16x16x32_bf16 v[14:17], v[110:113], v[204:207], v[14:17]
	v_mfma_f32_16x16x32_bf16 v[66:69], v[102:105], v[170:173], v[66:69]
	v_mfma_f32_16x16x32_bf16 v[62:65], v[114:117], v[170:173], v[62:65]
	v_mfma_f32_16x16x32_bf16 v[50:53], v[102:105], v[178:181], v[50:53]
	v_mfma_f32_16x16x32_bf16 v[46:49], v[114:117], v[178:181], v[46:49]
	v_mfma_f32_16x16x32_bf16 v[34:37], v[102:105], v[200:203], v[34:37]
	v_mfma_f32_16x16x32_bf16 v[30:33], v[114:117], v[200:203], v[30:33]
	v_mfma_f32_16x16x32_bf16 v[18:21], v[102:105], v[208:211], v[18:21]
	v_mfma_f32_16x16x32_bf16 v[14:17], v[114:117], v[208:211], v[14:17]
	s_setprio 0
	s_setprio 1
	v_mfma_f32_16x16x32_bf16 v[58:61], v[150:153], v[166:169], v[58:61]
	v_mfma_f32_16x16x32_bf16 v[54:57], v[158:161], v[166:169], v[54:57]
	v_mfma_f32_16x16x32_bf16 v[42:45], v[150:153], v[174:177], v[42:45]
	v_mfma_f32_16x16x32_bf16 v[38:41], v[158:161], v[174:177], v[38:41]
	v_mfma_f32_16x16x32_bf16 v[26:29], v[150:153], v[196:199], v[26:29]
	v_mfma_f32_16x16x32_bf16 v[22:25], v[158:161], v[196:199], v[22:25]
	v_mfma_f32_16x16x32_bf16 v[10:13], v[150:153], v[204:207], v[10:13]
	v_mfma_f32_16x16x32_bf16 v[6:9], v[158:161], v[204:207], v[6:9]
	v_mfma_f32_16x16x32_bf16 v[58:61], v[154:157], v[170:173], v[58:61]
	v_mfma_f32_16x16x32_bf16 v[54:57], v[162:165], v[170:173], v[54:57]
	v_mfma_f32_16x16x32_bf16 v[42:45], v[154:157], v[178:181], v[42:45]
	v_mfma_f32_16x16x32_bf16 v[38:41], v[162:165], v[178:181], v[38:41]
	v_mfma_f32_16x16x32_bf16 v[26:29], v[154:157], v[200:203], v[26:29]
	v_mfma_f32_16x16x32_bf16 v[22:25], v[162:165], v[200:203], v[22:25]
	v_mfma_f32_16x16x32_bf16 v[10:13], v[154:157], v[208:211], v[10:13]
	v_mfma_f32_16x16x32_bf16 v[6:9], v[162:165], v[208:211], v[6:9]
	s_setprio 0
	s_barrier
	s_add_i32 s45, 0, 0x18000
	v_add_u32_e32 v114, s45, v217
	v_add_u32_e32 v162, 0x1c000, v217
	ds_read_b128 v[94:97], v114
	ds_read_b128 v[102:105], v114 offset:1024
	ds_read_b128 v[110:113], v114 offset:2048
	ds_read_b128 v[114:117], v114 offset:3072
	ds_read_b128 v[150:153], v162
	ds_read_b128 v[154:157], v162 offset:1024
	ds_read_b128 v[158:161], v162 offset:2048
	ds_read_b128 v[162:165], v162 offset:3072
	s_add_u32 s26, s26, s42
	s_addc_u32 s27, s27, 0
	s_mov_b32 m0, s59
	ds_read_b128 v[166:169], v236 offset:32768
	ds_read_b128 v[170:173], v236 offset:33792
	ds_read_b128 v[174:177], v236 offset:34816
	ds_read_b128 v[178:181], v236 offset:35840
	ds_read_b128 v[196:199], v236 offset:36864
	ds_read_b128 v[200:203], v236 offset:37888
	ds_read_b128 v[204:207], v236 offset:38912
	ds_read_b128 v[208:211], v236 offset:39936
	global_load_lds_dwordx4 v182, s[26:27]
	s_mov_b32 m0, s62
	s_nop 0
	global_load_lds_dwordx4 v188, s[26:27]
	s_waitcnt vmcnt(8)
	s_waitcnt lgkmcnt(0)
	s_barrier
	s_setprio 1
	s_waitcnt lgkmcnt(0)
	v_mfma_f32_16x16x32_bf16 v[146:149], v[94:97], v[166:169], v[146:149]
	v_mfma_f32_16x16x32_bf16 v[142:145], v[110:113], v[166:169], v[142:145]
	v_mfma_f32_16x16x32_bf16 v[130:133], v[94:97], v[174:177], v[130:133]
	v_mfma_f32_16x16x32_bf16 v[126:129], v[110:113], v[174:177], v[126:129]
	v_mfma_f32_16x16x32_bf16 v[106:109], v[94:97], v[196:199], v[106:109]
	v_mfma_f32_16x16x32_bf16 v[98:101], v[110:113], v[196:199], v[98:101]
	v_mfma_f32_16x16x32_bf16 v[82:85], v[94:97], v[204:207], v[82:85]
	v_mfma_f32_16x16x32_bf16 v[78:81], v[110:113], v[204:207], v[78:81]
	v_mfma_f32_16x16x32_bf16 v[146:149], v[102:105], v[170:173], v[146:149]
	v_mfma_f32_16x16x32_bf16 v[142:145], v[114:117], v[170:173], v[142:145]
	v_mfma_f32_16x16x32_bf16 v[130:133], v[102:105], v[178:181], v[130:133]
	v_mfma_f32_16x16x32_bf16 v[126:129], v[114:117], v[178:181], v[126:129]
	v_mfma_f32_16x16x32_bf16 v[106:109], v[102:105], v[200:203], v[106:109]
	v_mfma_f32_16x16x32_bf16 v[98:101], v[114:117], v[200:203], v[98:101]
	v_mfma_f32_16x16x32_bf16 v[82:85], v[102:105], v[208:211], v[82:85]
	v_mfma_f32_16x16x32_bf16 v[78:81], v[114:117], v[208:211], v[78:81]
	s_setprio 0
	s_setprio 1
	v_mfma_f32_16x16x32_bf16 v[138:141], v[150:153], v[166:169], v[138:141]
	v_mfma_f32_16x16x32_bf16 v[134:137], v[158:161], v[166:169], v[134:137]
	v_mfma_f32_16x16x32_bf16 v[122:125], v[150:153], v[174:177], v[122:125]
	v_mfma_f32_16x16x32_bf16 v[118:121], v[158:161], v[174:177], v[118:121]
	v_mfma_f32_16x16x32_bf16 v[90:93], v[150:153], v[196:199], v[90:93]
	v_mfma_f32_16x16x32_bf16 v[86:89], v[158:161], v[196:199], v[86:89]
	v_mfma_f32_16x16x32_bf16 v[74:77], v[150:153], v[204:207], v[74:77]
	v_mfma_f32_16x16x32_bf16 v[70:73], v[158:161], v[204:207], v[70:73]
	v_mfma_f32_16x16x32_bf16 v[138:141], v[154:157], v[170:173], v[138:141]
	v_mfma_f32_16x16x32_bf16 v[134:137], v[162:165], v[170:173], v[134:137]
	v_mfma_f32_16x16x32_bf16 v[122:125], v[154:157], v[178:181], v[122:125]
	v_mfma_f32_16x16x32_bf16 v[118:121], v[162:165], v[178:181], v[118:121]
	v_mfma_f32_16x16x32_bf16 v[90:93], v[154:157], v[200:203], v[90:93]
	v_mfma_f32_16x16x32_bf16 v[86:89], v[162:165], v[200:203], v[86:89]
	v_mfma_f32_16x16x32_bf16 v[74:77], v[154:157], v[208:211], v[74:77]
	v_mfma_f32_16x16x32_bf16 v[70:73], v[162:165], v[208:211], v[70:73]
	s_setprio 0
	s_barrier
	s_add_i32 s32, s45, s54
	s_mov_b32 m0, s32
	ds_read_b128 v[166:169], v236 offset:49152
	ds_read_b128 v[170:173], v236 offset:50176
	ds_read_b128 v[174:177], v236 offset:51200
	ds_read_b128 v[178:181], v236 offset:52224
	ds_read_b128 v[196:199], v236 offset:53248
	ds_read_b128 v[200:203], v236 offset:54272
	ds_read_b128 v[204:207], v236 offset:55296
	ds_read_b128 v[208:211], v236 offset:56320
	global_load_lds_dwordx4 v0, s[100:101]
	s_add_i32 m0, s32, 0x2000
	s_add_i32 s32, s54, 0x1c000
	global_load_lds_dwordx4 v190, s[100:101]
	s_add_u32 s70, s70, 0x80
	s_addc_u32 s71, s71, 0
	s_mov_b32 m0, s32
	s_add_i32 s32, s32, 0x2000
	global_load_lds_dwordx4 v0, s[70:71]
	s_mov_b32 m0, s32
	s_sub_u32 s26, s26, s42
	s_subb_u32 s27, s27, 0
	global_load_lds_dwordx4 v190, s[70:71]
	s_add_u32 s26, s26, 0x80
	s_addc_u32 s27, s27, 0
	s_mov_b32 m0, s63
	s_nop 0
	global_load_lds_dwordx4 v182, s[26:27]
	s_mov_b32 m0, s66
	s_nop 0
	global_load_lds_dwordx4 v188, s[26:27]
	s_waitcnt vmcnt(8)
	s_waitcnt lgkmcnt(0)
	s_barrier
	s_setprio 1
	s_waitcnt lgkmcnt(0)
	v_mfma_f32_16x16x32_bf16 v[66:69], v[94:97], v[166:169], v[66:69]
	v_mfma_f32_16x16x32_bf16 v[62:65], v[110:113], v[166:169], v[62:65]
	v_mfma_f32_16x16x32_bf16 v[50:53], v[94:97], v[174:177], v[50:53]
	v_mfma_f32_16x16x32_bf16 v[46:49], v[110:113], v[174:177], v[46:49]
	v_mfma_f32_16x16x32_bf16 v[34:37], v[94:97], v[196:199], v[34:37]
	v_mfma_f32_16x16x32_bf16 v[30:33], v[110:113], v[196:199], v[30:33]
	v_mfma_f32_16x16x32_bf16 v[18:21], v[94:97], v[204:207], v[18:21]
	v_mfma_f32_16x16x32_bf16 v[14:17], v[110:113], v[204:207], v[14:17]
	v_mfma_f32_16x16x32_bf16 v[66:69], v[102:105], v[170:173], v[66:69]
	v_mfma_f32_16x16x32_bf16 v[62:65], v[114:117], v[170:173], v[62:65]
	v_mfma_f32_16x16x32_bf16 v[50:53], v[102:105], v[178:181], v[50:53]
	v_mfma_f32_16x16x32_bf16 v[46:49], v[114:117], v[178:181], v[46:49]
	v_mfma_f32_16x16x32_bf16 v[34:37], v[102:105], v[200:203], v[34:37]
	v_mfma_f32_16x16x32_bf16 v[30:33], v[114:117], v[200:203], v[30:33]
	v_mfma_f32_16x16x32_bf16 v[18:21], v[102:105], v[208:211], v[18:21]
	v_mfma_f32_16x16x32_bf16 v[14:17], v[114:117], v[208:211], v[14:17]
	s_setprio 0
	s_setprio 1
	v_mfma_f32_16x16x32_bf16 v[58:61], v[150:153], v[166:169], v[58:61]
	v_mfma_f32_16x16x32_bf16 v[54:57], v[158:161], v[166:169], v[54:57]
	v_mfma_f32_16x16x32_bf16 v[42:45], v[150:153], v[174:177], v[42:45]
	v_mfma_f32_16x16x32_bf16 v[38:41], v[158:161], v[174:177], v[38:41]
	v_mfma_f32_16x16x32_bf16 v[26:29], v[150:153], v[196:199], v[26:29]
	v_mfma_f32_16x16x32_bf16 v[22:25], v[158:161], v[196:199], v[22:25]
	v_mfma_f32_16x16x32_bf16 v[10:13], v[150:153], v[204:207], v[10:13]
	v_mfma_f32_16x16x32_bf16 v[6:9], v[158:161], v[204:207], v[6:9]
	v_mfma_f32_16x16x32_bf16 v[58:61], v[154:157], v[170:173], v[58:61]
	v_mfma_f32_16x16x32_bf16 v[54:57], v[162:165], v[170:173], v[54:57]
	v_mfma_f32_16x16x32_bf16 v[42:45], v[154:157], v[178:181], v[42:45]
	v_mfma_f32_16x16x32_bf16 v[38:41], v[162:165], v[178:181], v[38:41]
	v_mfma_f32_16x16x32_bf16 v[26:29], v[154:157], v[200:203], v[26:29]
	v_mfma_f32_16x16x32_bf16 v[22:25], v[162:165], v[200:203], v[22:25]
	v_mfma_f32_16x16x32_bf16 v[10:13], v[154:157], v[208:211], v[10:13]
	v_mfma_f32_16x16x32_bf16 v[6:9], v[162:165], v[208:211], v[6:9]
	s_setprio 0
	s_barrier
	s_add_u32 s10, s10, 0x100
	s_addc_u32 s11, s11, 0
	s_add_u32 s30, s30, 0x100
	s_addc_u32 s31, s31, 0
	s_cmp_ge_u32 s44, s67
	s_mov_b32 s26, s44
	s_cbranch_scc0 .LBB0_1065
	s_and_b64 vcc, exec, s[20:21]
	s_cbranch_vccnz .LBB0_1096
	s_mov_b64 s[30:31], 0
	s_andn2_b64 vcc, exec, s[22:23]
	s_mov_b64 s[26:27], 0
	s_cbranch_vccz .LBB0_1097

	.amdhsa_kernel _Z14fwd_megakernel6Params
		.amdhsa_group_segment_fixed_size 0
		.amdhsa_private_segment_fixed_size 0
		.amdhsa_kernarg_size 432
		.amdhsa_user_sgpr_count 2
		.amdhsa_user_sgpr_dispatch_ptr 0
		.amdhsa_user_sgpr_queue_ptr 0
		.amdhsa_user_sgpr_kernarg_segment_ptr 1
		.amdhsa_user_sgpr_dispatch_id 0
		.amdhsa_user_sgpr_kernarg_preload_length 0
		.amdhsa_user_sgpr_kernarg_preload_offset 0
		.amdhsa_user_sgpr_private_segment_size 0
		.amdhsa_uses_dynamic_stack 0
		.amdhsa_enable_private_segment 0
		.amdhsa_system_sgpr_workgroup_id_x 1
		.amdhsa_system_sgpr_workgroup_id_y 0
		.amdhsa_system_sgpr_workgroup_id_z 0
		.amdhsa_system_sgpr_workgroup_info 0
		.amdhsa_system_vgpr_workitem_id 2
		.amdhsa_next_free_vgpr 256
		.amdhsa_next_free_sgpr 102
		.amdhsa_accum_offset 256
		.amdhsa_reserve_vcc 1
		.amdhsa_float_round_mode_32 0
		.amdhsa_float_round_mode_16_64 0
		.amdhsa_float_denorm_mode_32 3
		.amdhsa_float_denorm_mode_16_64 3
		.amdhsa_dx10_clamp 1
		.amdhsa_ieee_mode 1
		.amdhsa_fp16_overflow 0
		.amdhsa_tg_split 0
		.amdhsa_exception_fp_ieee_invalid_op 0
		.amdhsa_exception_fp_denorm_src 0
		.amdhsa_exception_fp_ieee_div_zero 0
		.amdhsa_exception_fp_ieee_overflow 0
		.amdhsa_exception_fp_ieee_underflow 0
		.amdhsa_exception_fp_ieee_inexact 0
		.amdhsa_exception_int_div_zero 0
	.end_amdhsa_kernel

amdhsa.kernels:
  - .agpr_count:     0
    .args:
      - .offset:         0
        .size:           176
        .value_kind:     by_value
      - .offset:         176
        .size:           4
        .value_kind:     hidden_block_count_x
      - .offset:         180
        .size:           4
        .value_kind:     hidden_block_count_y
      - .offset:         184
        .size:           4
        .value_kind:     hidden_block_count_z
      - .offset:         188
        .size:           2
        .value_kind:     hidden_group_size_x
      - .offset:         190
        .size:           2
        .value_kind:     hidden_group_size_y
      - .offset:         192
        .size:           2
        .value_kind:     hidden_group_size_z
      - .offset:         194
        .size:           2
        .value_kind:     hidden_remainder_x
      - .offset:         196
        .size:           2
        .value_kind:     hidden_remainder_y
      - .offset:         198
        .size:           2
        .value_kind:     hidden_remainder_z
      - .offset:         216
        .size:           8
        .value_kind:     hidden_global_offset_x
      - .offset:         224
        .size:           8
        .value_kind:     hidden_global_offset_y
      - .offset:         232
        .size:           8
        .value_kind:     hidden_global_offset_z
      - .offset:         240
        .size:           2
        .value_kind:     hidden_grid_dims
      - .offset:         264
        .size:           8
        .value_kind:     hidden_multigrid_sync_arg
      - .offset:         296
        .size:           4
        .value_kind:     hidden_dynamic_lds_size
    .group_segment_fixed_size: 0
    .kernarg_segment_align: 8
    .kernarg_segment_size: 432
    .language:       OpenCL C
    .language_version:
      - 2
      - 0
    .max_flat_workgroup_size: 512
    .name:           _Z14fwd_megakernel6Params
    .private_segment_fixed_size: 0
    .sgpr_count:     108
    .sgpr_spill_count: 110
    .symbol:         _Z14fwd_megakernel6Params.kd
    .uniform_work_group_size: 1
    .uses_dynamic_stack: false
    .vgpr_count:     256
    .vgpr_spill_count: 0
    .wavefront_size: 64
